# DF unit epilogue: subln_g loads hoisted out of the 16 row bodies (no per-row vmcnt waits on stores), 128 2-byte stores widened to 32 dwordx2 via quad transposes; plus DPP row reductions and widened SB
# speedup vs baseline: 1.0037x; 1.0004x over previous
; #define LAS __attribute__((address_space(3)))
; __device__ __forceinline__ bf16_t f2bf(float f) { unsigned u = __float_as_uint(f); u += 0x7FFFu + ((u >> 16) & 1u); return (bf16_t)(u >> 16); }
; __device__ __forceinline__ void df_unit(LAS unsigned char* lds, const bf16_t* qkv, bf16_t* attout, const float* subg, int b_, int h_, int qb_, int wid, int) {
;     ...
;     if (jsel == 0) {
;         bf16_t* op = attout + (size_t)(b * SEQ + q0 + 4 * hi) * DM + 1024 + h * 256 + r32; const LAS float* xr = xb + (4 * hi) * 256 + r32;
; #pragma unroll
;         for (int r = 0; r < 16; ++r) { const int rowc = (r & 3) + 8 * (r >> 2); float ss = 0.f;
; #pragma unroll
;             for (int d = 0; d < 8; ++d) { o[d][r] -= xr[rowc * 256 + d * 32]; ss += o[d][r] * o[d][r]; }
;             ss += __shfl_xor(ss, 1); ss += __shfl_xor(ss, 2); ss += __shfl_xor(ss, 4); ss += __shfl_xor(ss, 8); ss += __shfl_xor(ss, 16);
;             const float rstd = (1.0f - LAMBDA_INIT) / sqrtf(ss * (1.0f / 256.0f) + SUBLN_EPS);
; #pragma unroll
;             for (int d = 0; d < 8; ++d) op[d * 32] = f2bf(o[d][r] * rstd * subg[d * 32 + r32]);
;             op += ((r & 3) == 3 ? 5 : 1) * DM; asm volatile("" : "+v"(op) :: "memory"); } }
.LBB0_299:
	s_waitcnt vmcnt(0) lgkmcnt(0)
	s_barrier
	s_andn2_b64 vcc, exec, s[10:11]
	s_cbranch_vccnz .LBB0_260
	v_lshlrev_b32_e32 v3, 12, v193
	v_lshlrev_b32_e32 v13, 2, v178
	v_add3_u32 v13, s53, v3, v13
	ds_read2_b32 v[32:33], v13 offset1:32
	v_ashrrev_i32_e32 v179, 31, v178
	ds_read2_b32 v[46:47], v13 offset0:64 offset1:96
	s_lshl_b32 s0, s33, 12
	s_add_i32 s42, s42, s0
	s_waitcnt lgkmcnt(1)
	v_sub_f32_e32 v17, v177, v32
	v_sub_f32_e32 v31, v180, v33
	ds_read2_b32 v[32:33], v13 offset0:128 offset1:160
	v_mul_f32_e32 v48, v31, v31
	s_waitcnt lgkmcnt(1)
	v_sub_f32_e32 v49, v176, v46
	v_sub_f32_e32 v60, v175, v47
	ds_read2_b32 v[46:47], v13 offset0:192 offset1:224
	s_waitcnt lgkmcnt(1)
	v_sub_f32_e32 v61, v2, v32
	v_lshl_add_u64 v[2:3], v[178:179], 2, s[58:59]
	global_load_dword v194, v[2:3], off
	global_load_dword v195, v[2:3], off offset:128
	global_load_dword v196, v[2:3], off offset:256
	global_load_dword v197, v[2:3], off offset:384
	global_load_dword v198, v[2:3], off offset:512
	global_load_dword v199, v[2:3], off offset:640
	global_load_dword v200, v[2:3], off offset:768
	global_load_dword v201, v[2:3], off offset:896
	s_waitcnt vmcnt(0)
	v_mov_b32_e32 v62, v194
	v_mov_b32_e32 v64, v195
	v_mov_b32_e32 v65, v196
	v_mov_b32_e32 v75, v197
	v_mov_b32_e32 v76, v199
	v_mov_b32_e32 v77, v200
	v_mov_b32_e32 v78, v201
	v_fmac_f32_e32 v48, v17, v17
	v_fmac_f32_e32 v48, v49, v49
	v_fmac_f32_e32 v48, v60, v60
	v_fmac_f32_e32 v48, v61, v61
	v_sub_f32_e32 v63, v174, v33
	v_fmac_f32_e32 v48, v63, v63
	s_waitcnt lgkmcnt(0)
	v_sub_f32_e32 v46, v173, v46
	v_fmac_f32_e32 v48, v46, v46
	v_sub_f32_e32 v47, v172, v47
	v_fmac_f32_e32 v48, v47, v47
	s_nop 1
	v_mov_b32_dpp v32, v48 quad_perm:[1,0,3,2] row_mask:0xf bank_mask:0xf
	s_waitcnt lgkmcnt(0)
	v_add_f32_e32 v32, v48, v32
	v_mov_b32_e32 v48, v198
	s_nop 1
	v_mov_b32_dpp v33, v32 quad_perm:[2,3,0,1] row_mask:0xf bank_mask:0xf
	s_waitcnt lgkmcnt(0)
	v_add_f32_e32 v32, v32, v33
	s_nop 1
	v_mov_b32_dpp v33, v32 row_half_mirror row_mask:0xf bank_mask:0xf
	s_waitcnt lgkmcnt(0)
	v_add_f32_e32 v32, v32, v33
	s_nop 1
	v_mov_b32_dpp v33, v32 row_mirror row_mask:0xf bank_mask:0xf
	s_waitcnt lgkmcnt(0)
	v_add_f32_e32 v32, v32, v33
	v_mov_b32_e32 v33, v32
	s_nop 1
	v_permlane16_swap_b32_e32 v33, v32
	s_waitcnt lgkmcnt(0)
	v_add_f32_e32 v32, v32, v33
	v_fmamk_f32 v32, v32, 0x3b800000, v190
	v_mul_f32_e32 v33, 0x4f800000, v32
	v_cmp_gt_f32_e32 vcc, s56, v32
	s_nop 1
	v_cndmask_b32_e32 v79, v32, v33, vcc
	v_sqrt_f32_e32 v80, v79
	v_lshl_add_u32 v32, v193, 2, s42
	v_ashrrev_i32_e32 v33, 31, v32
	v_lshlrev_b64 v[32:33], 12, v[32:33]
	v_add_u32_e32 v81, -1, v80
	v_fma_f32 v90, -v81, v80, v79
	v_cmp_ge_f32_e64 s[0:1], 0, v90
	v_add_u32_e32 v90, 1, v80
	v_lshl_add_u64 v[32:33], s[44:45], 0, v[32:33]
	v_cndmask_b32_e64 v81, v80, v81, s[0:1]
	v_fma_f32 v80, -v90, v80, v79
	v_cmp_lt_f32_e64 s[0:1], 0, v80
	v_lshl_add_u64 v[32:33], s[26:27], 1, v[32:33]
	v_lshl_add_u64 v[32:33], v[178:179], 1, v[32:33]
	v_cndmask_b32_e64 v80, v81, v90, s[0:1]
	v_mul_f32_e32 v81, 0x37800000, v80
	v_cndmask_b32_e32 v80, v80, v81, vcc
	v_cmp_class_f32_e32 vcc, v79, v189
	s_nop 1
	v_cndmask_b32_e32 v79, v80, v79, vcc
	v_div_scale_f32 v80, s[0:1], v79, v79, s87
	v_rcp_f32_e32 v81, v80
	s_nop 0
	v_fma_f32 v90, -v80, v81, 1.0
	v_fmac_f32_e32 v81, v90, v81
	v_div_scale_f32 v90, vcc, s87, v79, s87
	v_mul_f32_e32 v91, v90, v81
	v_fma_f32 v92, -v80, v91, v90
	v_fmac_f32_e32 v91, v92, v81
	v_fma_f32 v80, -v80, v91, v90
	v_div_fmas_f32 v80, v80, v81, v91
	v_div_fixup_f32 v79, v80, v79, s87
	v_mul_f32_e32 v17, v17, v79
	v_mul_f32_e32 v17, v62, v17
	v_mov_b32_e32 v222, v17
	v_mul_f32_e32 v17, v31, v79
	v_mul_f32_e32 v17, v64, v17
	v_mov_b32_e32 v226, v17
	v_mul_f32_e32 v17, v49, v79
	v_mul_f32_e32 v17, v65, v17
	v_mov_b32_e32 v230, v17
	v_mul_f32_e32 v17, v60, v79
	v_mul_f32_e32 v17, v75, v17
	v_mov_b32_e32 v234, v17
	v_mul_f32_e32 v17, v61, v79
	v_mul_f32_e32 v17, v48, v17
	v_mov_b32_e32 v238, v17
	v_mul_f32_e32 v17, v63, v79
	v_mul_f32_e32 v17, v17, v76
	v_mov_b32_e32 v242, v17
	v_mul_f32_e32 v17, v46, v79
	v_mul_f32_e32 v17, v17, v77
	v_mov_b32_e32 v246, v17
	v_mul_f32_e32 v17, v47, v79
	v_mul_f32_e32 v17, v17, v78
	v_mov_b32_e32 v250, v17
	v_lshl_add_u64 v[32:33], v[32:33], 0, s[12:13]
	v_add_u32_e32 v17, 0x400, v13
	ds_read2_b32 v[46:47], v17 offset1:32
	ds_read2_b32 v[48:49], v17 offset0:64 offset1:96
	v_mov_b32_e32 v64, v194
	v_mov_b32_e32 v65, v196
	v_mov_b32_e32 v76, v197
	v_mov_b32_e32 v77, v198
	v_mov_b32_e32 v78, v199
	v_mov_b32_e32 v79, v200
	s_waitcnt lgkmcnt(1)
	v_sub_f32_e32 v31, v171, v46
	v_sub_f32_e32 v60, v170, v47
	ds_read2_b32 v[46:47], v17 offset0:128 offset1:160
	v_mul_f32_e32 v61, v60, v60
	s_waitcnt lgkmcnt(1)
	v_sub_f32_e32 v62, v169, v48
	v_sub_f32_e32 v63, v168, v49
	ds_read2_b32 v[48:49], v17 offset0:192 offset1:224
	v_fmac_f32_e32 v61, v31, v31
	v_fmac_f32_e32 v61, v62, v62
	v_fmac_f32_e32 v61, v63, v63
	s_waitcnt lgkmcnt(1)
	v_sub_f32_e32 v46, v167, v46
	v_fmac_f32_e32 v61, v46, v46
	v_sub_f32_e32 v17, v166, v47
	v_fmac_f32_e32 v61, v17, v17
	s_waitcnt lgkmcnt(0)
	v_sub_f32_e32 v48, v165, v48
	v_fmac_f32_e32 v61, v48, v48
	v_sub_f32_e32 v49, v164, v49
	v_fmac_f32_e32 v61, v49, v49
	s_nop 1
	v_mov_b32_dpp v75, v61 quad_perm:[1,0,3,2] row_mask:0xf bank_mask:0xf
	v_mov_b32_e32 v47, v195
	s_waitcnt lgkmcnt(0)
	v_add_f32_e32 v61, v61, v75
	s_nop 1
	v_mov_b32_dpp v75, v61 quad_perm:[2,3,0,1] row_mask:0xf bank_mask:0xf
	s_waitcnt lgkmcnt(0)
	v_add_f32_e32 v61, v61, v75
	s_nop 1
	v_mov_b32_dpp v75, v61 row_half_mirror row_mask:0xf bank_mask:0xf
	s_waitcnt lgkmcnt(0)
; #define LAS __attribute__((address_space(3)))
; __device__ __forceinline__ bf16_t f2bf(float f) { unsigned u = __float_as_uint(f); u += 0x7FFFu + ((u >> 16) & 1u); return (bf16_t)(u >> 16); }
; __device__ __forceinline__ void df_unit(LAS unsigned char* lds, const bf16_t* qkv, bf16_t* attout, const float* subg, int b_, int h_, int qb_, int wid, int) {
;     ...
;     if (jsel == 0) {
;         bf16_t* op = attout + (size_t)(b * SEQ + q0 + 4 * hi) * DM + 1024 + h * 256 + r32; const LAS float* xr = xb + (4 * hi) * 256 + r32;
; #pragma unroll
;         for (int r = 0; r < 16; ++r) { const int rowc = (r & 3) + 8 * (r >> 2); float ss = 0.f;
; #pragma unroll
;             for (int d = 0; d < 8; ++d) { o[d][r] -= xr[rowc * 256 + d * 32]; ss += o[d][r] * o[d][r]; }
;             ss += __shfl_xor(ss, 1); ss += __shfl_xor(ss, 2); ss += __shfl_xor(ss, 4); ss += __shfl_xor(ss, 8); ss += __shfl_xor(ss, 16);
;             const float rstd = (1.0f - LAMBDA_INIT) / sqrtf(ss * (1.0f / 256.0f) + SUBLN_EPS);
; #pragma unroll
;             for (int d = 0; d < 8; ++d) op[d * 32] = f2bf(o[d][r] * rstd * subg[d * 32 + r32]);
;             op += ((r & 3) == 3 ? 5 : 1) * DM; asm volatile("" : "+v"(op) :: "memory"); } }
	v_add_f32_e32 v61, v61, v75
	s_nop 1
	v_mov_b32_dpp v75, v61 row_mirror row_mask:0xf bank_mask:0xf
	s_waitcnt lgkmcnt(0)
	v_add_f32_e32 v61, v61, v75
	v_mov_b32_e32 v75, v201
	v_mov_b32_e32 v80, v61
	s_nop 1
	v_permlane16_swap_b32_e32 v80, v61
	s_waitcnt lgkmcnt(0)
	v_add_f32_e32 v61, v61, v80
	v_fmamk_f32 v61, v61, 0x3b800000, v190
	v_mul_f32_e32 v80, 0x4f800000, v61
	v_cmp_gt_f32_e32 vcc, s56, v61
	s_nop 1
	v_cndmask_b32_e32 v61, v61, v80, vcc
	v_sqrt_f32_e32 v80, v61
	s_nop 0
	v_add_u32_e32 v81, -1, v80
	v_fma_f32 v90, -v81, v80, v61
	v_cmp_ge_f32_e64 s[0:1], 0, v90
	v_add_u32_e32 v90, 1, v80
	s_nop 0
	v_cndmask_b32_e64 v81, v80, v81, s[0:1]
	v_fma_f32 v80, -v90, v80, v61
	v_cmp_lt_f32_e64 s[0:1], 0, v80
	s_nop 1
	v_cndmask_b32_e64 v80, v81, v90, s[0:1]
	v_mul_f32_e32 v81, 0x37800000, v80
	v_cndmask_b32_e32 v80, v80, v81, vcc
	v_cmp_class_f32_e32 vcc, v61, v189
	s_nop 1
	v_cndmask_b32_e32 v61, v80, v61, vcc
	v_div_scale_f32 v80, s[0:1], v61, v61, s87
	v_rcp_f32_e32 v81, v80
	s_nop 0
	v_fma_f32 v90, -v80, v81, 1.0
	v_fmac_f32_e32 v81, v90, v81
	v_div_scale_f32 v90, vcc, s87, v61, s87
	v_mul_f32_e32 v91, v90, v81
	v_fma_f32 v92, -v80, v91, v90
	v_fmac_f32_e32 v91, v92, v81
	v_fma_f32 v80, -v80, v91, v90
	v_div_fmas_f32 v80, v80, v81, v91
	v_div_fixup_f32 v61, v80, v61, s87
	v_mul_f32_e32 v31, v31, v61
	v_mul_f32_e32 v31, v64, v31
	v_mov_b32_e32 v223, v31
	v_mul_f32_e32 v31, v60, v61
	v_mul_f32_e32 v17, v17, v61
	v_mul_f32_e32 v31, v47, v31
	v_mov_b32_e32 v227, v31
	v_mul_f32_e32 v31, v62, v61
	v_mul_f32_e32 v31, v65, v31
	v_mov_b32_e32 v231, v31
	v_mul_f32_e32 v31, v63, v61
	v_mul_f32_e32 v31, v76, v31
	v_mov_b32_e32 v235, v31
	v_mul_f32_e32 v31, v46, v61
	v_mul_f32_e32 v31, v77, v31
	v_mov_b32_e32 v239, v31
	v_mul_f32_e32 v17, v17, v78
	v_mov_b32_e32 v243, v17
	v_mul_f32_e32 v17, v48, v61
	v_mul_f32_e32 v17, v17, v79
	v_mov_b32_e32 v247, v17
	v_mul_f32_e32 v17, v49, v61
	v_mul_f32_e32 v17, v17, v75
	v_mov_b32_e32 v251, v17
	v_lshl_add_u64 v[32:33], v[32:33], 0, s[20:21]
	v_add_u32_e32 v17, 0x800, v13
	ds_read2_b32 v[46:47], v17 offset1:32
	ds_read2_b32 v[48:49], v17 offset0:64 offset1:96
	v_mov_b32_e32 v64, v194
	v_mov_b32_e32 v65, v196
	v_mov_b32_e32 v76, v197
	v_mov_b32_e32 v77, v198
	v_mov_b32_e32 v78, v199
	v_mov_b32_e32 v79, v200
	s_waitcnt lgkmcnt(0)
	v_sub_f32_e32 v31, v163, v46
	v_sub_f32_e32 v60, v162, v47
	ds_read2_b32 v[46:47], v17 offset0:128 offset1:160
	v_mul_f32_e32 v61, v60, v60
	v_sub_f32_e32 v62, v161, v48
	v_sub_f32_e32 v63, v160, v49
	ds_read2_b32 v[48:49], v17 offset0:192 offset1:224
	v_fmac_f32_e32 v61, v31, v31
	v_fmac_f32_e32 v61, v62, v62
	v_fmac_f32_e32 v61, v63, v63
	s_waitcnt lgkmcnt(0)
	v_sub_f32_e32 v46, v159, v46
	v_fmac_f32_e32 v61, v46, v46
	v_sub_f32_e32 v17, v158, v47
	v_fmac_f32_e32 v61, v17, v17
	v_sub_f32_e32 v48, v157, v48
	v_fmac_f32_e32 v61, v48, v48
	v_sub_f32_e32 v49, v156, v49
	v_fmac_f32_e32 v61, v49, v49
	s_nop 1
	v_mov_b32_dpp v75, v61 quad_perm:[1,0,3,2] row_mask:0xf bank_mask:0xf
	v_mov_b32_e32 v47, v195
	s_waitcnt lgkmcnt(0)
	v_add_f32_e32 v61, v61, v75
	s_nop 1
	v_mov_b32_dpp v75, v61 quad_perm:[2,3,0,1] row_mask:0xf bank_mask:0xf
	s_waitcnt lgkmcnt(0)
	v_add_f32_e32 v61, v61, v75
	s_nop 1
	v_mov_b32_dpp v75, v61 row_half_mirror row_mask:0xf bank_mask:0xf
	s_waitcnt lgkmcnt(0)
	v_add_f32_e32 v61, v61, v75
	s_nop 1
	v_mov_b32_dpp v75, v61 row_mirror row_mask:0xf bank_mask:0xf
	s_waitcnt lgkmcnt(0)
	v_add_f32_e32 v61, v61, v75
	v_mov_b32_e32 v75, v201
	v_mov_b32_e32 v80, v61
	s_nop 1
	v_permlane16_swap_b32_e32 v80, v61
	s_waitcnt lgkmcnt(0)
	v_add_f32_e32 v61, v61, v80
	v_fmamk_f32 v61, v61, 0x3b800000, v190
	v_mul_f32_e32 v80, 0x4f800000, v61
	v_cmp_gt_f32_e32 vcc, s56, v61
	s_nop 1
	v_cndmask_b32_e32 v61, v61, v80, vcc
	v_sqrt_f32_e32 v80, v61
	s_nop 0
	v_add_u32_e32 v81, -1, v80
	v_fma_f32 v90, -v81, v80, v61
	v_cmp_ge_f32_e64 s[0:1], 0, v90
	v_add_u32_e32 v90, 1, v80
	s_nop 0
	v_cndmask_b32_e64 v81, v80, v81, s[0:1]
	v_fma_f32 v80, -v90, v80, v61
	v_cmp_lt_f32_e64 s[0:1], 0, v80
	s_nop 1
	v_cndmask_b32_e64 v80, v81, v90, s[0:1]
	v_mul_f32_e32 v81, 0x37800000, v80
	v_cndmask_b32_e32 v80, v80, v81, vcc
	v_cmp_class_f32_e32 vcc, v61, v189
	s_nop 1
	v_cndmask_b32_e32 v61, v80, v61, vcc
	v_div_scale_f32 v80, s[0:1], v61, v61, s87
	v_rcp_f32_e32 v81, v80
	s_nop 0
	v_fma_f32 v90, -v80, v81, 1.0
	v_fmac_f32_e32 v81, v90, v81
	v_div_scale_f32 v90, vcc, s87, v61, s87
	v_mul_f32_e32 v91, v90, v81
	v_fma_f32 v92, -v80, v91, v90
	v_fmac_f32_e32 v91, v92, v81
	v_fma_f32 v80, -v80, v91, v90
	v_div_fmas_f32 v80, v80, v81, v91
	v_div_fixup_f32 v61, v80, v61, s87
	v_mul_f32_e32 v31, v31, v61
	v_mul_f32_e32 v31, v64, v31
	v_mov_b32_e32 v224, v31
	v_mul_f32_e32 v31, v60, v61
	v_mul_f32_e32 v17, v17, v61
	v_mul_f32_e32 v31, v47, v31
	v_mov_b32_e32 v228, v31
	v_mul_f32_e32 v31, v62, v61
	v_mul_f32_e32 v31, v65, v31
	v_mov_b32_e32 v232, v31
	v_mul_f32_e32 v31, v63, v61
	v_mul_f32_e32 v31, v76, v31
	v_mov_b32_e32 v236, v31
	v_mul_f32_e32 v31, v46, v61
	v_mul_f32_e32 v31, v77, v31
	v_mov_b32_e32 v240, v31
	v_mul_f32_e32 v17, v17, v78
	v_mov_b32_e32 v244, v17
	v_mul_f32_e32 v17, v48, v61
	v_mul_f32_e32 v17, v17, v79
	v_mov_b32_e32 v248, v17
	v_mul_f32_e32 v17, v49, v61
	v_mul_f32_e32 v17, v17, v75
	v_mov_b32_e32 v252, v17
	v_lshl_add_u64 v[32:33], v[32:33], 0, s[20:21]
	v_add_u32_e32 v17, 0xc00, v13
	ds_read2_b32 v[46:47], v17 offset1:32
	ds_read2_b32 v[48:49], v17 offset0:64 offset1:96
	v_mov_b32_e32 v64, v194
	v_mov_b32_e32 v65, v196
	v_mov_b32_e32 v76, v197
	v_mov_b32_e32 v77, v198
	v_mov_b32_e32 v78, v199
	v_mov_b32_e32 v79, v200
	s_waitcnt lgkmcnt(0)
; #define LAS __attribute__((address_space(3)))
; __device__ __forceinline__ bf16_t f2bf(float f) { unsigned u = __float_as_uint(f); u += 0x7FFFu + ((u >> 16) & 1u); return (bf16_t)(u >> 16); }
; __device__ __forceinline__ void df_unit(LAS unsigned char* lds, const bf16_t* qkv, bf16_t* attout, const float* subg, int b_, int h_, int qb_, int wid, int) {
;     ...
;         bf16_t* op = attout + (size_t)(b * SEQ + q0 + 4 * hi) * DM + 1024 + h * 256 + r32; const LAS float* xr = xb + (4 * hi) * 256 + r32;
; #pragma unroll
;         for (int r = 0; r < 16; ++r) { const int rowc = (r & 3) + 8 * (r >> 2); float ss = 0.f;
; #pragma unroll
;             for (int d = 0; d < 8; ++d) { o[d][r] -= xr[rowc * 256 + d * 32]; ss += o[d][r] * o[d][r]; }
;             ss += __shfl_xor(ss, 1); ss += __shfl_xor(ss, 2); ss += __shfl_xor(ss, 4); ss += __shfl_xor(ss, 8); ss += __shfl_xor(ss, 16);
;             const float rstd = (1.0f - LAMBDA_INIT) / sqrtf(ss * (1.0f / 256.0f) + SUBLN_EPS);
; #pragma unroll
;             for (int d = 0; d < 8; ++d) op[d * 32] = f2bf(o[d][r] * rstd * subg[d * 32 + r32]);
;             op += ((r & 3) == 3 ? 5 : 1) * DM; asm volatile("" : "+v"(op) :: "memory"); } }
	v_sub_f32_e32 v31, v155, v46
	v_sub_f32_e32 v60, v154, v47
	ds_read2_b32 v[46:47], v17 offset0:128 offset1:160
	v_mul_f32_e32 v61, v60, v60
	v_sub_f32_e32 v62, v153, v48
	v_sub_f32_e32 v63, v152, v49
	ds_read2_b32 v[48:49], v17 offset0:192 offset1:224
	v_fmac_f32_e32 v61, v31, v31
	v_fmac_f32_e32 v61, v62, v62
	v_fmac_f32_e32 v61, v63, v63
	s_waitcnt lgkmcnt(0)
	v_sub_f32_e32 v46, v151, v46
	v_fmac_f32_e32 v61, v46, v46
	v_sub_f32_e32 v17, v150, v47
	v_fmac_f32_e32 v61, v17, v17
	v_sub_f32_e32 v48, v149, v48
	v_fmac_f32_e32 v61, v48, v48
	v_sub_f32_e32 v49, v148, v49
	v_fmac_f32_e32 v61, v49, v49
	s_nop 1
	v_mov_b32_dpp v75, v61 quad_perm:[1,0,3,2] row_mask:0xf bank_mask:0xf
	v_mov_b32_e32 v47, v195
	s_waitcnt lgkmcnt(0)
	v_add_f32_e32 v61, v61, v75
	s_nop 1
	v_mov_b32_dpp v75, v61 quad_perm:[2,3,0,1] row_mask:0xf bank_mask:0xf
	s_waitcnt lgkmcnt(0)
	v_add_f32_e32 v61, v61, v75
	s_nop 1
	v_mov_b32_dpp v75, v61 row_half_mirror row_mask:0xf bank_mask:0xf
	s_waitcnt lgkmcnt(0)
	v_add_f32_e32 v61, v61, v75
	s_nop 1
	v_mov_b32_dpp v75, v61 row_mirror row_mask:0xf bank_mask:0xf
	s_waitcnt lgkmcnt(0)
	v_add_f32_e32 v61, v61, v75
	v_mov_b32_e32 v75, v201
	v_mov_b32_e32 v80, v61
	s_nop 1
	v_permlane16_swap_b32_e32 v80, v61
	s_waitcnt lgkmcnt(0)
	v_add_f32_e32 v61, v61, v80
	v_fmamk_f32 v61, v61, 0x3b800000, v190
	v_mul_f32_e32 v80, 0x4f800000, v61
	v_cmp_gt_f32_e32 vcc, s56, v61
	s_nop 1
	v_cndmask_b32_e32 v61, v61, v80, vcc
	v_sqrt_f32_e32 v80, v61
	s_nop 0
	v_add_u32_e32 v81, -1, v80
	v_fma_f32 v90, -v81, v80, v61
	v_cmp_ge_f32_e64 s[0:1], 0, v90
	v_add_u32_e32 v90, 1, v80
	s_nop 0
	v_cndmask_b32_e64 v81, v80, v81, s[0:1]
	v_fma_f32 v80, -v90, v80, v61
	v_cmp_lt_f32_e64 s[0:1], 0, v80
	s_nop 1
	v_cndmask_b32_e64 v80, v81, v90, s[0:1]
	v_mul_f32_e32 v81, 0x37800000, v80
	v_cndmask_b32_e32 v80, v80, v81, vcc
	v_cmp_class_f32_e32 vcc, v61, v189
	s_nop 1
	v_cndmask_b32_e32 v61, v80, v61, vcc
	v_div_scale_f32 v80, s[0:1], v61, v61, s87
	v_rcp_f32_e32 v81, v80
	s_nop 0
	v_fma_f32 v90, -v80, v81, 1.0
	v_fmac_f32_e32 v81, v90, v81
	v_div_scale_f32 v90, vcc, s87, v61, s87
	v_mul_f32_e32 v91, v90, v81
	v_fma_f32 v92, -v80, v91, v90
	v_fmac_f32_e32 v91, v92, v81
	v_fma_f32 v80, -v80, v91, v90
	v_div_fmas_f32 v80, v80, v81, v91
	v_div_fixup_f32 v61, v80, v61, s87
	v_mul_f32_e32 v31, v31, v61
	v_mul_f32_e32 v31, v64, v31
	v_mov_b32_e32 v225, v31
	v_mul_f32_e32 v31, v60, v61
	v_mul_f32_e32 v17, v17, v61
	v_mul_f32_e32 v31, v47, v31
	v_mov_b32_e32 v229, v31
	v_mul_f32_e32 v31, v62, v61
	v_mul_f32_e32 v31, v65, v31
	v_mov_b32_e32 v233, v31
	v_mul_f32_e32 v31, v63, v61
	v_mul_f32_e32 v31, v76, v31
	v_mov_b32_e32 v237, v31
	v_mul_f32_e32 v31, v46, v61
	v_mul_f32_e32 v31, v77, v31
	v_mov_b32_e32 v241, v31
	v_mul_f32_e32 v17, v17, v78
	v_mov_b32_e32 v245, v17
	v_mul_f32_e32 v17, v48, v61
	v_mul_f32_e32 v17, v17, v79
	v_mov_b32_e32 v249, v17
	v_mul_f32_e32 v17, v49, v61
	v_mul_f32_e32 v17, v17, v75
	v_mov_b32_e32 v253, v17
	v_lshl_add_u32 v202, v193, 2, s42
	v_and_b32_e32 v205, 3, v178
	v_add_u32_e32 v202, v202, v205
	v_ashrrev_i32_e32 v203, 31, v202
	v_lshlrev_b64 v[202:203], 12, v[202:203]
	v_lshl_add_u64 v[202:203], s[44:45], 0, v[202:203]
	v_lshl_add_u64 v[202:203], s[26:27], 1, v[202:203]
	v_and_b32_e32 v204, 28, v178
	v_mov_b32_e32 v205, 0
	v_lshl_add_u64 v[202:203], v[204:205], 1, v[202:203]
	v_and_b32_e32 v204, 1, v178
	v_sub_u32_e32 v204, 0, v204
	v_and_b32_e32 v204, 0x6060606, v204
	s_mov_b32 s98, 0xcccccccc
	s_mov_b32 s99, 0xcccccccc
	s_mov_b64 s[100:101], 0x8000
	v_xor_b32_e32 v204, 0x1000504, v204
	v_cvt_pk_bf16_f32 v222, v222, v223
	v_cvt_pk_bf16_f32 v226, v226, v227
	v_cvt_pk_bf16_f32 v230, v230, v231
	v_cvt_pk_bf16_f32 v234, v234, v235
	v_cvt_pk_bf16_f32 v238, v238, v239
	v_cvt_pk_bf16_f32 v242, v242, v243
	v_cvt_pk_bf16_f32 v246, v246, v247
	v_cvt_pk_bf16_f32 v250, v250, v251
	v_cvt_pk_bf16_f32 v224, v224, v225
	v_cvt_pk_bf16_f32 v228, v228, v229
	v_cvt_pk_bf16_f32 v232, v232, v233
	v_cvt_pk_bf16_f32 v236, v236, v237
	v_cvt_pk_bf16_f32 v240, v240, v241
	v_cvt_pk_bf16_f32 v244, v244, v245
	v_cvt_pk_bf16_f32 v248, v248, v249
	v_cvt_pk_bf16_f32 v252, v252, v253
	v_mov_b32_dpp v223, v222 quad_perm:[1,0,3,2] row_mask:0xf bank_mask:0xf
	v_mov_b32_dpp v227, v226 quad_perm:[1,0,3,2] row_mask:0xf bank_mask:0xf
	v_mov_b32_dpp v231, v230 quad_perm:[1,0,3,2] row_mask:0xf bank_mask:0xf
	v_mov_b32_dpp v235, v234 quad_perm:[1,0,3,2] row_mask:0xf bank_mask:0xf
	v_mov_b32_dpp v239, v238 quad_perm:[1,0,3,2] row_mask:0xf bank_mask:0xf
	v_mov_b32_dpp v243, v242 quad_perm:[1,0,3,2] row_mask:0xf bank_mask:0xf
	v_mov_b32_dpp v247, v246 quad_perm:[1,0,3,2] row_mask:0xf bank_mask:0xf
	v_mov_b32_dpp v251, v250 quad_perm:[1,0,3,2] row_mask:0xf bank_mask:0xf
	v_mov_b32_dpp v225, v224 quad_perm:[1,0,3,2] row_mask:0xf bank_mask:0xf
	v_mov_b32_dpp v229, v228 quad_perm:[1,0,3,2] row_mask:0xf bank_mask:0xf
	v_mov_b32_dpp v233, v232 quad_perm:[1,0,3,2] row_mask:0xf bank_mask:0xf
	v_mov_b32_dpp v237, v236 quad_perm:[1,0,3,2] row_mask:0xf bank_mask:0xf
	v_mov_b32_dpp v241, v240 quad_perm:[1,0,3,2] row_mask:0xf bank_mask:0xf
	v_mov_b32_dpp v245, v244 quad_perm:[1,0,3,2] row_mask:0xf bank_mask:0xf
	v_mov_b32_dpp v249, v248 quad_perm:[1,0,3,2] row_mask:0xf bank_mask:0xf
	v_mov_b32_dpp v253, v252 quad_perm:[1,0,3,2] row_mask:0xf bank_mask:0xf
	v_perm_b32 v222, v222, v223, v204
	v_perm_b32 v226, v226, v227, v204
	v_perm_b32 v230, v230, v231, v204
	v_perm_b32 v234, v234, v235, v204
	v_perm_b32 v238, v238, v239, v204
	v_perm_b32 v242, v242, v243, v204
	v_perm_b32 v246, v246, v247, v204
	v_perm_b32 v250, v250, v251, v204
	v_perm_b32 v224, v224, v225, v204
	v_perm_b32 v228, v228, v229, v204
; __device__ __forceinline__ bf16_t f2bf(float f) { unsigned u = __float_as_uint(f); u += 0x7FFFu + ((u >> 16) & 1u); return (bf16_t)(u >> 16); }
; __device__ __forceinline__ void df_unit(LAS unsigned char* lds, const bf16_t* qkv, bf16_t* attout, const float* subg, int b_, int h_, int qb_, int wid, int) {
;     ...
;         for (int r = 0; r < 16; ++r) { const int rowc = (r & 3) + 8 * (r >> 2); float ss = 0.f;
; #pragma unroll
;             for (int d = 0; d < 8; ++d) { o[d][r] -= xr[rowc * 256 + d * 32]; ss += o[d][r] * o[d][r]; }
;             ss += __shfl_xor(ss, 1); ss += __shfl_xor(ss, 2); ss += __shfl_xor(ss, 4); ss += __shfl_xor(ss, 8); ss += __shfl_xor(ss, 16);
;             const float rstd = (1.0f - LAMBDA_INIT) / sqrtf(ss * (1.0f / 256.0f) + SUBLN_EPS);
; #pragma unroll
;             for (int d = 0; d < 8; ++d) op[d * 32] = f2bf(o[d][r] * rstd * subg[d * 32 + r32]);
;             op += ((r & 3) == 3 ? 5 : 1) * DM; asm volatile("" : "+v"(op) :: "memory"); } }
	v_perm_b32 v232, v232, v233, v204
	v_perm_b32 v236, v236, v237, v204
	v_perm_b32 v240, v240, v241, v204
	v_perm_b32 v244, v244, v245, v204
	v_perm_b32 v248, v248, v249, v204
	v_perm_b32 v252, v252, v253, v204
	v_cndmask_b32_e64 v223, v224, v222, s[98:99]
	v_cndmask_b32_e64 v227, v228, v226, s[98:99]
	v_cndmask_b32_e64 v231, v232, v230, s[98:99]
	v_cndmask_b32_e64 v235, v236, v234, s[98:99]
	v_cndmask_b32_e64 v239, v240, v238, s[98:99]
	v_cndmask_b32_e64 v243, v244, v242, s[98:99]
	v_cndmask_b32_e64 v247, v248, v246, s[98:99]
	v_cndmask_b32_e64 v251, v252, v250, s[98:99]
	v_mov_b32_dpp v225, v223 quad_perm:[2,3,0,1] row_mask:0xf bank_mask:0xf
	v_mov_b32_dpp v229, v227 quad_perm:[2,3,0,1] row_mask:0xf bank_mask:0xf
	v_mov_b32_dpp v233, v231 quad_perm:[2,3,0,1] row_mask:0xf bank_mask:0xf
	v_mov_b32_dpp v237, v235 quad_perm:[2,3,0,1] row_mask:0xf bank_mask:0xf
	v_mov_b32_dpp v241, v239 quad_perm:[2,3,0,1] row_mask:0xf bank_mask:0xf
	v_mov_b32_dpp v245, v243 quad_perm:[2,3,0,1] row_mask:0xf bank_mask:0xf
	v_mov_b32_dpp v249, v247 quad_perm:[2,3,0,1] row_mask:0xf bank_mask:0xf
	v_mov_b32_dpp v253, v251 quad_perm:[2,3,0,1] row_mask:0xf bank_mask:0xf
	v_cndmask_b32_e64 v223, v225, v224, s[98:99]
	v_cndmask_b32_e64 v227, v229, v228, s[98:99]
	v_cndmask_b32_e64 v231, v233, v232, s[98:99]
	v_cndmask_b32_e64 v235, v237, v236, s[98:99]
	v_cndmask_b32_e64 v239, v241, v240, s[98:99]
	v_cndmask_b32_e64 v243, v245, v244, s[98:99]
	v_cndmask_b32_e64 v247, v249, v248, s[98:99]
	v_cndmask_b32_e64 v251, v253, v252, s[98:99]
	v_cndmask_b32_e64 v222, v222, v225, s[98:99]
	v_cndmask_b32_e64 v226, v226, v229, s[98:99]
	v_cndmask_b32_e64 v230, v230, v233, s[98:99]
	v_cndmask_b32_e64 v234, v234, v237, s[98:99]
	v_cndmask_b32_e64 v238, v238, v241, s[98:99]
	v_cndmask_b32_e64 v242, v242, v245, s[98:99]
	v_cndmask_b32_e64 v246, v246, v249, s[98:99]
	v_cndmask_b32_e64 v250, v250, v253, s[98:99]
	global_store_dwordx2 v[202:203], v[222:223], off offset:2048
	global_store_dwordx2 v[202:203], v[226:227], off offset:2112
	global_store_dwordx2 v[202:203], v[230:231], off offset:2176
	global_store_dwordx2 v[202:203], v[234:235], off offset:2240
	global_store_dwordx2 v[202:203], v[238:239], off offset:2304
	global_store_dwordx2 v[202:203], v[242:243], off offset:2368
	global_store_dwordx2 v[202:203], v[246:247], off offset:2432
	global_store_dwordx2 v[202:203], v[250:251], off offset:2496
	v_lshl_add_u64 v[202:203], v[202:203], 0, s[100:101]
	v_lshl_add_u64 v[32:33], v[32:33], 0, s[22:23]
	v_add_u32_e32 v17, 0x2000, v13
	ds_read2_b32 v[46:47], v17 offset1:32
	ds_read2_b32 v[48:49], v17 offset0:64 offset1:96
	v_mov_b32_e32 v64, v194
	v_mov_b32_e32 v65, v196
	v_mov_b32_e32 v76, v197
	v_mov_b32_e32 v77, v198
	v_mov_b32_e32 v78, v199
	v_mov_b32_e32 v79, v200
	s_waitcnt lgkmcnt(0)
	v_sub_f32_e32 v31, v147, v46
	v_sub_f32_e32 v60, v146, v47
	ds_read2_b32 v[46:47], v17 offset0:128 offset1:160
	v_mul_f32_e32 v61, v60, v60
	v_sub_f32_e32 v62, v145, v48
	v_sub_f32_e32 v63, v144, v49
	ds_read2_b32 v[48:49], v17 offset0:192 offset1:224
	v_fmac_f32_e32 v61, v31, v31
	v_fmac_f32_e32 v61, v62, v62
	v_fmac_f32_e32 v61, v63, v63
	s_waitcnt lgkmcnt(0)
	v_sub_f32_e32 v46, v143, v46
	v_fmac_f32_e32 v61, v46, v46
	v_sub_f32_e32 v17, v142, v47
	v_fmac_f32_e32 v61, v17, v17
	v_sub_f32_e32 v48, v141, v48
	v_fmac_f32_e32 v61, v48, v48
	v_sub_f32_e32 v49, v140, v49
	v_fmac_f32_e32 v61, v49, v49
	s_nop 1
	v_mov_b32_dpp v75, v61 quad_perm:[1,0,3,2] row_mask:0xf bank_mask:0xf
	v_mov_b32_e32 v47, v195
	s_waitcnt lgkmcnt(0)
	v_add_f32_e32 v61, v61, v75
	s_nop 1
	v_mov_b32_dpp v75, v61 quad_perm:[2,3,0,1] row_mask:0xf bank_mask:0xf
	s_waitcnt lgkmcnt(0)
	v_add_f32_e32 v61, v61, v75
	s_nop 1
	v_mov_b32_dpp v75, v61 row_half_mirror row_mask:0xf bank_mask:0xf
	s_waitcnt lgkmcnt(0)
	v_add_f32_e32 v61, v61, v75
	s_nop 1
	v_mov_b32_dpp v75, v61 row_mirror row_mask:0xf bank_mask:0xf
	s_waitcnt lgkmcnt(0)
	v_add_f32_e32 v61, v61, v75
	v_mov_b32_e32 v75, v201
	v_mov_b32_e32 v80, v61
	s_nop 1
	v_permlane16_swap_b32_e32 v80, v61
	s_waitcnt lgkmcnt(0)
	v_add_f32_e32 v61, v61, v80
	v_fmamk_f32 v61, v61, 0x3b800000, v190
	v_mul_f32_e32 v80, 0x4f800000, v61
	v_cmp_gt_f32_e32 vcc, s56, v61
	s_nop 1
	v_cndmask_b32_e32 v61, v61, v80, vcc
	v_sqrt_f32_e32 v80, v61
	s_nop 0
	v_add_u32_e32 v81, -1, v80
	v_fma_f32 v90, -v81, v80, v61
	v_cmp_ge_f32_e64 s[0:1], 0, v90
	v_add_u32_e32 v90, 1, v80
	s_nop 0
	v_cndmask_b32_e64 v81, v80, v81, s[0:1]
	v_fma_f32 v80, -v90, v80, v61
	v_cmp_lt_f32_e64 s[0:1], 0, v80
	s_nop 1
	v_cndmask_b32_e64 v80, v81, v90, s[0:1]
	v_mul_f32_e32 v81, 0x37800000, v80
	v_cndmask_b32_e32 v80, v80, v81, vcc
	v_cmp_class_f32_e32 vcc, v61, v189
	s_nop 1
	v_cndmask_b32_e32 v61, v80, v61, vcc
	v_div_scale_f32 v80, s[0:1], v61, v61, s87
	v_rcp_f32_e32 v81, v80
	s_nop 0
	v_fma_f32 v90, -v80, v81, 1.0
	v_fmac_f32_e32 v81, v90, v81
	v_div_scale_f32 v90, vcc, s87, v61, s87
	v_mul_f32_e32 v91, v90, v81
	v_fma_f32 v92, -v80, v91, v90
	v_fmac_f32_e32 v91, v92, v81
	v_fma_f32 v80, -v80, v91, v90
	v_div_fmas_f32 v80, v80, v81, v91
	v_div_fixup_f32 v61, v80, v61, s87
	v_mul_f32_e32 v31, v31, v61
	v_mul_f32_e32 v31, v64, v31
	v_mov_b32_e32 v222, v31
	v_mul_f32_e32 v31, v60, v61
	v_mul_f32_e32 v17, v17, v61
	v_mul_f32_e32 v31, v47, v31
	v_mov_b32_e32 v226, v31
	v_mul_f32_e32 v31, v62, v61
	v_mul_f32_e32 v31, v65, v31
	v_mov_b32_e32 v230, v31
	v_mul_f32_e32 v31, v63, v61
	v_mul_f32_e32 v31, v76, v31
	v_mov_b32_e32 v234, v31
	v_mul_f32_e32 v31, v46, v61
	v_mul_f32_e32 v31, v77, v31
	v_mov_b32_e32 v238, v31
	v_mul_f32_e32 v17, v17, v78
	v_mov_b32_e32 v242, v17
	v_mul_f32_e32 v17, v48, v61
	v_mul_f32_e32 v17, v17, v79
	v_mov_b32_e32 v246, v17
	v_mul_f32_e32 v17, v49, v61
	v_mul_f32_e32 v17, v17, v75
	v_mov_b32_e32 v250, v17
	v_lshl_add_u64 v[32:33], v[32:33], 0, s[20:21]
	v_add_u32_e32 v17, 0x2400, v13
	ds_read2_b32 v[46:47], v17 offset1:32
	ds_read2_b32 v[48:49], v17 offset0:64 offset1:96
	v_mov_b32_e32 v64, v194
	v_mov_b32_e32 v65, v196
	v_mov_b32_e32 v76, v197
	v_mov_b32_e32 v77, v198
	v_mov_b32_e32 v78, v199
	v_mov_b32_e32 v79, v200
	s_waitcnt lgkmcnt(0)
; __device__ __forceinline__ bf16_t f2bf(float f) { unsigned u = __float_as_uint(f); u += 0x7FFFu + ((u >> 16) & 1u); return (bf16_t)(u >> 16); }
; __device__ __forceinline__ void df_unit(LAS unsigned char* lds, const bf16_t* qkv, bf16_t* attout, const float* subg, int b_, int h_, int qb_, int wid, int) {
;     ...
;         for (int r = 0; r < 16; ++r) { const int rowc = (r & 3) + 8 * (r >> 2); float ss = 0.f;
; #pragma unroll
;             for (int d = 0; d < 8; ++d) { o[d][r] -= xr[rowc * 256 + d * 32]; ss += o[d][r] * o[d][r]; }
;             ss += __shfl_xor(ss, 1); ss += __shfl_xor(ss, 2); ss += __shfl_xor(ss, 4); ss += __shfl_xor(ss, 8); ss += __shfl_xor(ss, 16);
;             const float rstd = (1.0f - LAMBDA_INIT) / sqrtf(ss * (1.0f / 256.0f) + SUBLN_EPS);
; #pragma unroll
;             for (int d = 0; d < 8; ++d) op[d * 32] = f2bf(o[d][r] * rstd * subg[d * 32 + r32]);
;             op += ((r & 3) == 3 ? 5 : 1) * DM; asm volatile("" : "+v"(op) :: "memory"); } }
	v_sub_f32_e32 v31, v139, v46
	v_sub_f32_e32 v60, v138, v47
	ds_read2_b32 v[46:47], v17 offset0:128 offset1:160
	v_mul_f32_e32 v61, v60, v60
	v_sub_f32_e32 v62, v137, v48
	v_sub_f32_e32 v63, v136, v49
	ds_read2_b32 v[48:49], v17 offset0:192 offset1:224
	v_fmac_f32_e32 v61, v31, v31
	v_fmac_f32_e32 v61, v62, v62
	v_fmac_f32_e32 v61, v63, v63
	s_waitcnt lgkmcnt(0)
	v_sub_f32_e32 v46, v135, v46
	v_fmac_f32_e32 v61, v46, v46
	v_sub_f32_e32 v17, v134, v47
	v_fmac_f32_e32 v61, v17, v17
	v_sub_f32_e32 v48, v133, v48
	v_fmac_f32_e32 v61, v48, v48
	v_sub_f32_e32 v49, v132, v49
	v_fmac_f32_e32 v61, v49, v49
	s_nop 1
	v_mov_b32_dpp v75, v61 quad_perm:[1,0,3,2] row_mask:0xf bank_mask:0xf
	v_mov_b32_e32 v47, v195
	s_waitcnt lgkmcnt(0)
	v_add_f32_e32 v61, v61, v75
	s_nop 1
	v_mov_b32_dpp v75, v61 quad_perm:[2,3,0,1] row_mask:0xf bank_mask:0xf
	s_waitcnt lgkmcnt(0)
	v_add_f32_e32 v61, v61, v75
	s_nop 1
	v_mov_b32_dpp v75, v61 row_half_mirror row_mask:0xf bank_mask:0xf
	s_waitcnt lgkmcnt(0)
	v_add_f32_e32 v61, v61, v75
	s_nop 1
	v_mov_b32_dpp v75, v61 row_mirror row_mask:0xf bank_mask:0xf
	s_waitcnt lgkmcnt(0)
	v_add_f32_e32 v61, v61, v75
	v_mov_b32_e32 v75, v201
	v_mov_b32_e32 v80, v61
	s_nop 1
	v_permlane16_swap_b32_e32 v80, v61
	s_waitcnt lgkmcnt(0)
	v_add_f32_e32 v61, v61, v80
	v_fmamk_f32 v61, v61, 0x3b800000, v190
	v_mul_f32_e32 v80, 0x4f800000, v61
	v_cmp_gt_f32_e32 vcc, s56, v61
	s_nop 1
	v_cndmask_b32_e32 v61, v61, v80, vcc
	v_sqrt_f32_e32 v80, v61
	s_nop 0
	v_add_u32_e32 v81, -1, v80
	v_fma_f32 v90, -v81, v80, v61
	v_cmp_ge_f32_e64 s[0:1], 0, v90
	v_add_u32_e32 v90, 1, v80
	s_nop 0
	v_cndmask_b32_e64 v81, v80, v81, s[0:1]
	v_fma_f32 v80, -v90, v80, v61
	v_cmp_lt_f32_e64 s[0:1], 0, v80
	s_nop 1
	v_cndmask_b32_e64 v80, v81, v90, s[0:1]
	v_mul_f32_e32 v81, 0x37800000, v80
	v_cndmask_b32_e32 v80, v80, v81, vcc
	v_cmp_class_f32_e32 vcc, v61, v189
	s_nop 1
	v_cndmask_b32_e32 v61, v80, v61, vcc
	v_div_scale_f32 v80, s[0:1], v61, v61, s87
	v_rcp_f32_e32 v81, v80
	s_nop 0
	v_fma_f32 v90, -v80, v81, 1.0
	v_fmac_f32_e32 v81, v90, v81
	v_div_scale_f32 v90, vcc, s87, v61, s87
	v_mul_f32_e32 v91, v90, v81
	v_fma_f32 v92, -v80, v91, v90
	v_fmac_f32_e32 v91, v92, v81
	v_fma_f32 v80, -v80, v91, v90
	v_div_fmas_f32 v80, v80, v81, v91
	v_div_fixup_f32 v61, v80, v61, s87
	v_mul_f32_e32 v31, v31, v61
	v_mul_f32_e32 v31, v64, v31
	v_mov_b32_e32 v223, v31
	v_mul_f32_e32 v31, v60, v61
	v_mul_f32_e32 v17, v17, v61
	v_mul_f32_e32 v31, v47, v31
	v_mov_b32_e32 v227, v31
	v_mul_f32_e32 v31, v62, v61
	v_mul_f32_e32 v31, v65, v31
	v_mov_b32_e32 v231, v31
	v_mul_f32_e32 v31, v63, v61
	v_mul_f32_e32 v31, v76, v31
	v_mov_b32_e32 v235, v31
	v_mul_f32_e32 v31, v46, v61
	v_mul_f32_e32 v31, v77, v31
	v_mov_b32_e32 v239, v31
	v_mul_f32_e32 v17, v17, v78
	v_mov_b32_e32 v243, v17
	v_mul_f32_e32 v17, v48, v61
	v_mul_f32_e32 v17, v17, v79
	v_mov_b32_e32 v247, v17
	v_mul_f32_e32 v17, v49, v61
	v_mul_f32_e32 v17, v17, v75
	v_mov_b32_e32 v251, v17
	v_lshl_add_u64 v[32:33], v[32:33], 0, s[20:21]
	v_add_u32_e32 v17, 0x2800, v13
	ds_read2_b32 v[46:47], v17 offset1:32
	ds_read2_b32 v[48:49], v17 offset0:64 offset1:96
	v_mov_b32_e32 v64, v194
	v_mov_b32_e32 v65, v196
	v_mov_b32_e32 v76, v197
	v_mov_b32_e32 v77, v198
	v_mov_b32_e32 v78, v199
	v_mov_b32_e32 v79, v200
	s_waitcnt lgkmcnt(0)
	v_sub_f32_e32 v31, v131, v46
	v_sub_f32_e32 v60, v130, v47
	ds_read2_b32 v[46:47], v17 offset0:128 offset1:160
	v_mul_f32_e32 v61, v60, v60
	v_sub_f32_e32 v62, v119, v48
	v_sub_f32_e32 v63, v118, v49
	ds_read2_b32 v[48:49], v17 offset0:192 offset1:224
	v_fmac_f32_e32 v61, v31, v31
	v_fmac_f32_e32 v61, v62, v62
	v_fmac_f32_e32 v61, v63, v63
	s_waitcnt lgkmcnt(0)
	v_sub_f32_e32 v46, v117, v46
	v_fmac_f32_e32 v61, v46, v46
	v_sub_f32_e32 v17, v116, v47
	v_fmac_f32_e32 v61, v17, v17
	v_sub_f32_e32 v48, v115, v48
	v_fmac_f32_e32 v61, v48, v48
	v_sub_f32_e32 v49, v114, v49
	v_fmac_f32_e32 v61, v49, v49
	s_nop 1
	v_mov_b32_dpp v75, v61 quad_perm:[1,0,3,2] row_mask:0xf bank_mask:0xf
	v_mov_b32_e32 v47, v195
	s_waitcnt lgkmcnt(0)
	v_add_f32_e32 v61, v61, v75
	s_nop 1
	v_mov_b32_dpp v75, v61 quad_perm:[2,3,0,1] row_mask:0xf bank_mask:0xf
	s_waitcnt lgkmcnt(0)
	v_add_f32_e32 v61, v61, v75
	s_nop 1
	v_mov_b32_dpp v75, v61 row_half_mirror row_mask:0xf bank_mask:0xf
	s_waitcnt lgkmcnt(0)
	v_add_f32_e32 v61, v61, v75
	s_nop 1
	v_mov_b32_dpp v75, v61 row_mirror row_mask:0xf bank_mask:0xf
	s_waitcnt lgkmcnt(0)
	v_add_f32_e32 v61, v61, v75
	v_mov_b32_e32 v75, v201
	v_mov_b32_e32 v80, v61
	s_nop 1
	v_permlane16_swap_b32_e32 v80, v61
	s_waitcnt lgkmcnt(0)
	v_add_f32_e32 v61, v61, v80
	v_fmamk_f32 v61, v61, 0x3b800000, v190
	v_mul_f32_e32 v80, 0x4f800000, v61
	v_cmp_gt_f32_e32 vcc, s56, v61
	s_nop 1
	v_cndmask_b32_e32 v61, v61, v80, vcc
	v_sqrt_f32_e32 v80, v61
	s_nop 0
	v_add_u32_e32 v81, -1, v80
	v_fma_f32 v90, -v81, v80, v61
	v_cmp_ge_f32_e64 s[0:1], 0, v90
	v_add_u32_e32 v90, 1, v80
	s_nop 0
	v_cndmask_b32_e64 v81, v80, v81, s[0:1]
	v_fma_f32 v80, -v90, v80, v61
	v_cmp_lt_f32_e64 s[0:1], 0, v80
	s_nop 1
	v_cndmask_b32_e64 v80, v81, v90, s[0:1]
	v_mul_f32_e32 v81, 0x37800000, v80
	v_cndmask_b32_e32 v80, v80, v81, vcc
	v_cmp_class_f32_e32 vcc, v61, v189
	s_nop 1
	v_cndmask_b32_e32 v61, v80, v61, vcc
	v_div_scale_f32 v80, s[0:1], v61, v61, s87
	v_rcp_f32_e32 v81, v80
	s_nop 0
	v_fma_f32 v90, -v80, v81, 1.0
	v_fmac_f32_e32 v81, v90, v81
	v_div_scale_f32 v90, vcc, s87, v61, s87
	v_mul_f32_e32 v91, v90, v81
	v_fma_f32 v92, -v80, v91, v90
	v_fmac_f32_e32 v91, v92, v81
	v_fma_f32 v80, -v80, v91, v90
	v_div_fmas_f32 v80, v80, v81, v91
	v_div_fixup_f32 v61, v80, v61, s87
	v_mul_f32_e32 v31, v31, v61
	v_mul_f32_e32 v31, v64, v31
	v_mov_b32_e32 v224, v31
	v_mul_f32_e32 v31, v60, v61
	v_mul_f32_e32 v17, v17, v61
	v_mul_f32_e32 v31, v47, v31
	v_mov_b32_e32 v228, v31
	v_mul_f32_e32 v31, v62, v61
	v_mul_f32_e32 v31, v65, v31
	v_mov_b32_e32 v232, v31
	v_mul_f32_e32 v31, v63, v61
	v_mul_f32_e32 v31, v76, v31
	v_mov_b32_e32 v236, v31
	v_mul_f32_e32 v31, v46, v61
	v_mul_f32_e32 v31, v77, v31
	v_mov_b32_e32 v240, v31
	v_mul_f32_e32 v17, v17, v78
	v_mov_b32_e32 v244, v17
	v_mul_f32_e32 v17, v48, v61
	v_mul_f32_e32 v17, v17, v79
	v_mov_b32_e32 v248, v17
	v_mul_f32_e32 v17, v49, v61
	v_mul_f32_e32 v17, v17, v75
	v_mov_b32_e32 v252, v17
	v_lshl_add_u64 v[32:33], v[32:33], 0, s[20:21]
	v_add_u32_e32 v17, 0x2c00, v13
	ds_read2_b32 v[46:47], v17 offset1:32
	ds_read2_b32 v[48:49], v17 offset0:64 offset1:96
	v_mov_b32_e32 v64, v194
	v_mov_b32_e32 v65, v196
	v_mov_b32_e32 v76, v197
	v_mov_b32_e32 v77, v198
	v_mov_b32_e32 v78, v199
	v_mov_b32_e32 v79, v200
	s_waitcnt lgkmcnt(0)
; __device__ __forceinline__ bf16_t f2bf(float f) { unsigned u = __float_as_uint(f); u += 0x7FFFu + ((u >> 16) & 1u); return (bf16_t)(u >> 16); }
; __device__ __forceinline__ void df_unit(LAS unsigned char* lds, const bf16_t* qkv, bf16_t* attout, const float* subg, int b_, int h_, int qb_, int wid, int) {
;     ...
;         for (int r = 0; r < 16; ++r) { const int rowc = (r & 3) + 8 * (r >> 2); float ss = 0.f;
; #pragma unroll
;             for (int d = 0; d < 8; ++d) { o[d][r] -= xr[rowc * 256 + d * 32]; ss += o[d][r] * o[d][r]; }
;             ss += __shfl_xor(ss, 1); ss += __shfl_xor(ss, 2); ss += __shfl_xor(ss, 4); ss += __shfl_xor(ss, 8); ss += __shfl_xor(ss, 16);
;             const float rstd = (1.0f - LAMBDA_INIT) / sqrtf(ss * (1.0f / 256.0f) + SUBLN_EPS);
; #pragma unroll
;             for (int d = 0; d < 8; ++d) op[d * 32] = f2bf(o[d][r] * rstd * subg[d * 32 + r32]);
;             op += ((r & 3) == 3 ? 5 : 1) * DM; asm volatile("" : "+v"(op) :: "memory"); } }
	v_sub_f32_e32 v31, v104, v46
	v_sub_f32_e32 v60, v103, v47
	ds_read2_b32 v[46:47], v17 offset0:128 offset1:160
	v_mul_f32_e32 v61, v60, v60
	v_sub_f32_e32 v62, v102, v48
	v_sub_f32_e32 v63, v101, v49
	ds_read2_b32 v[48:49], v17 offset0:192 offset1:224
	v_fmac_f32_e32 v61, v31, v31
	v_fmac_f32_e32 v61, v62, v62
	v_fmac_f32_e32 v61, v63, v63
	s_waitcnt lgkmcnt(0)
	v_sub_f32_e32 v46, v100, v46
	v_fmac_f32_e32 v61, v46, v46
	v_sub_f32_e32 v17, v99, v47
	v_fmac_f32_e32 v61, v17, v17
	v_sub_f32_e32 v48, v98, v48
	v_fmac_f32_e32 v61, v48, v48
	v_sub_f32_e32 v49, v89, v49
	v_fmac_f32_e32 v61, v49, v49
	s_nop 1
	v_mov_b32_dpp v75, v61 quad_perm:[1,0,3,2] row_mask:0xf bank_mask:0xf
	v_mov_b32_e32 v47, v195
	s_waitcnt lgkmcnt(0)
	v_add_f32_e32 v61, v61, v75
	s_nop 1
	v_mov_b32_dpp v75, v61 quad_perm:[2,3,0,1] row_mask:0xf bank_mask:0xf
	s_waitcnt lgkmcnt(0)
	v_add_f32_e32 v61, v61, v75
	s_nop 1
	v_mov_b32_dpp v75, v61 row_half_mirror row_mask:0xf bank_mask:0xf
	s_waitcnt lgkmcnt(0)
	v_add_f32_e32 v61, v61, v75
	s_nop 1
	v_mov_b32_dpp v75, v61 row_mirror row_mask:0xf bank_mask:0xf
	s_waitcnt lgkmcnt(0)
	v_add_f32_e32 v61, v61, v75
	v_mov_b32_e32 v75, v201
	v_mov_b32_e32 v80, v61
	s_nop 1
	v_permlane16_swap_b32_e32 v80, v61
	s_waitcnt lgkmcnt(0)
	v_add_f32_e32 v61, v61, v80
	v_fmamk_f32 v61, v61, 0x3b800000, v190
	v_mul_f32_e32 v80, 0x4f800000, v61
	v_cmp_gt_f32_e32 vcc, s56, v61
	s_nop 1
	v_cndmask_b32_e32 v61, v61, v80, vcc
	v_sqrt_f32_e32 v80, v61
	s_nop 0
	v_add_u32_e32 v81, -1, v80
	v_fma_f32 v89, -v81, v80, v61
	v_cmp_ge_f32_e64 s[0:1], 0, v89
	v_add_u32_e32 v89, 1, v80
	s_nop 0
	v_cndmask_b32_e64 v81, v80, v81, s[0:1]
	v_fma_f32 v80, -v89, v80, v61
	v_cmp_lt_f32_e64 s[0:1], 0, v80
	s_nop 1
	v_cndmask_b32_e64 v80, v81, v89, s[0:1]
	v_mul_f32_e32 v81, 0x37800000, v80
	v_cndmask_b32_e32 v80, v80, v81, vcc
	v_cmp_class_f32_e32 vcc, v61, v189
	s_nop 1
	v_cndmask_b32_e32 v61, v80, v61, vcc
	v_div_scale_f32 v80, s[0:1], v61, v61, s87
	v_rcp_f32_e32 v81, v80
	s_nop 0
	v_fma_f32 v89, -v80, v81, 1.0
	v_fmac_f32_e32 v81, v89, v81
	v_div_scale_f32 v89, vcc, s87, v61, s87
	v_mul_f32_e32 v90, v89, v81
	v_fma_f32 v91, -v80, v90, v89
	v_fmac_f32_e32 v90, v91, v81
	v_fma_f32 v80, -v80, v90, v89
	v_div_fmas_f32 v80, v80, v81, v90
	v_div_fixup_f32 v61, v80, v61, s87
	v_mul_f32_e32 v31, v31, v61
	v_mul_f32_e32 v31, v64, v31
	v_mov_b32_e32 v225, v31
	v_mul_f32_e32 v31, v60, v61
	v_mul_f32_e32 v17, v17, v61
	v_mul_f32_e32 v31, v47, v31
	v_mov_b32_e32 v229, v31
	v_mul_f32_e32 v31, v62, v61
	v_mul_f32_e32 v31, v65, v31
	v_mov_b32_e32 v233, v31
	v_mul_f32_e32 v31, v63, v61
	v_mul_f32_e32 v31, v76, v31
	v_mov_b32_e32 v237, v31
	v_mul_f32_e32 v31, v46, v61
	v_mul_f32_e32 v31, v77, v31
	v_mov_b32_e32 v241, v31
	v_mul_f32_e32 v17, v17, v78
	v_mov_b32_e32 v245, v17
	v_mul_f32_e32 v17, v48, v61
	v_mul_f32_e32 v17, v17, v79
	v_mov_b32_e32 v249, v17
	v_mul_f32_e32 v17, v49, v61
	v_mul_f32_e32 v17, v17, v75
	v_mov_b32_e32 v253, v17
	v_cvt_pk_bf16_f32 v222, v222, v223
	v_cvt_pk_bf16_f32 v226, v226, v227
	v_cvt_pk_bf16_f32 v230, v230, v231
	v_cvt_pk_bf16_f32 v234, v234, v235
	v_cvt_pk_bf16_f32 v238, v238, v239
	v_cvt_pk_bf16_f32 v242, v242, v243
	v_cvt_pk_bf16_f32 v246, v246, v247
	v_cvt_pk_bf16_f32 v250, v250, v251
	v_cvt_pk_bf16_f32 v224, v224, v225
	v_cvt_pk_bf16_f32 v228, v228, v229
	v_cvt_pk_bf16_f32 v232, v232, v233
	v_cvt_pk_bf16_f32 v236, v236, v237
	v_cvt_pk_bf16_f32 v240, v240, v241
	v_cvt_pk_bf16_f32 v244, v244, v245
	v_cvt_pk_bf16_f32 v248, v248, v249
	v_cvt_pk_bf16_f32 v252, v252, v253
	v_mov_b32_dpp v223, v222 quad_perm:[1,0,3,2] row_mask:0xf bank_mask:0xf
	v_mov_b32_dpp v227, v226 quad_perm:[1,0,3,2] row_mask:0xf bank_mask:0xf
	v_mov_b32_dpp v231, v230 quad_perm:[1,0,3,2] row_mask:0xf bank_mask:0xf
	v_mov_b32_dpp v235, v234 quad_perm:[1,0,3,2] row_mask:0xf bank_mask:0xf
	v_mov_b32_dpp v239, v238 quad_perm:[1,0,3,2] row_mask:0xf bank_mask:0xf
	v_mov_b32_dpp v243, v242 quad_perm:[1,0,3,2] row_mask:0xf bank_mask:0xf
	v_mov_b32_dpp v247, v246 quad_perm:[1,0,3,2] row_mask:0xf bank_mask:0xf
	v_mov_b32_dpp v251, v250 quad_perm:[1,0,3,2] row_mask:0xf bank_mask:0xf
	v_mov_b32_dpp v225, v224 quad_perm:[1,0,3,2] row_mask:0xf bank_mask:0xf
	v_mov_b32_dpp v229, v228 quad_perm:[1,0,3,2] row_mask:0xf bank_mask:0xf
	v_mov_b32_dpp v233, v232 quad_perm:[1,0,3,2] row_mask:0xf bank_mask:0xf
	v_mov_b32_dpp v237, v236 quad_perm:[1,0,3,2] row_mask:0xf bank_mask:0xf
	v_mov_b32_dpp v241, v240 quad_perm:[1,0,3,2] row_mask:0xf bank_mask:0xf
	v_mov_b32_dpp v245, v244 quad_perm:[1,0,3,2] row_mask:0xf bank_mask:0xf
	v_mov_b32_dpp v249, v248 quad_perm:[1,0,3,2] row_mask:0xf bank_mask:0xf
	v_mov_b32_dpp v253, v252 quad_perm:[1,0,3,2] row_mask:0xf bank_mask:0xf
	v_perm_b32 v222, v222, v223, v204
	v_perm_b32 v226, v226, v227, v204
	v_perm_b32 v230, v230, v231, v204
	v_perm_b32 v234, v234, v235, v204
	v_perm_b32 v238, v238, v239, v204
	v_perm_b32 v242, v242, v243, v204
	v_perm_b32 v246, v246, v247, v204
	v_perm_b32 v250, v250, v251, v204
	v_perm_b32 v224, v224, v225, v204
	v_perm_b32 v228, v228, v229, v204
	v_perm_b32 v232, v232, v233, v204
	v_perm_b32 v236, v236, v237, v204
	v_perm_b32 v240, v240, v241, v204
	v_perm_b32 v244, v244, v245, v204
	v_perm_b32 v248, v248, v249, v204
	v_perm_b32 v252, v252, v253, v204
	v_cndmask_b32_e64 v223, v224, v222, s[98:99]
	v_cndmask_b32_e64 v227, v228, v226, s[98:99]
	v_cndmask_b32_e64 v231, v232, v230, s[98:99]
	v_cndmask_b32_e64 v235, v236, v234, s[98:99]
	v_cndmask_b32_e64 v239, v240, v238, s[98:99]
	v_cndmask_b32_e64 v243, v244, v242, s[98:99]
	v_cndmask_b32_e64 v247, v248, v246, s[98:99]
	v_cndmask_b32_e64 v251, v252, v250, s[98:99]
; __device__ __forceinline__ bf16_t f2bf(float f) { unsigned u = __float_as_uint(f); u += 0x7FFFu + ((u >> 16) & 1u); return (bf16_t)(u >> 16); }
; __device__ __forceinline__ void df_unit(LAS unsigned char* lds, const bf16_t* qkv, bf16_t* attout, const float* subg, int b_, int h_, int qb_, int wid, int) {
;     ...
;         for (int r = 0; r < 16; ++r) { const int rowc = (r & 3) + 8 * (r >> 2); float ss = 0.f;
; #pragma unroll
;             for (int d = 0; d < 8; ++d) { o[d][r] -= xr[rowc * 256 + d * 32]; ss += o[d][r] * o[d][r]; }
;             ss += __shfl_xor(ss, 1); ss += __shfl_xor(ss, 2); ss += __shfl_xor(ss, 4); ss += __shfl_xor(ss, 8); ss += __shfl_xor(ss, 16);
;             const float rstd = (1.0f - LAMBDA_INIT) / sqrtf(ss * (1.0f / 256.0f) + SUBLN_EPS);
; #pragma unroll
;             for (int d = 0; d < 8; ++d) op[d * 32] = f2bf(o[d][r] * rstd * subg[d * 32 + r32]);
;             op += ((r & 3) == 3 ? 5 : 1) * DM; asm volatile("" : "+v"(op) :: "memory"); } }
	v_mov_b32_dpp v225, v223 quad_perm:[2,3,0,1] row_mask:0xf bank_mask:0xf
	v_mov_b32_dpp v229, v227 quad_perm:[2,3,0,1] row_mask:0xf bank_mask:0xf
	v_mov_b32_dpp v233, v231 quad_perm:[2,3,0,1] row_mask:0xf bank_mask:0xf
	v_mov_b32_dpp v237, v235 quad_perm:[2,3,0,1] row_mask:0xf bank_mask:0xf
	v_mov_b32_dpp v241, v239 quad_perm:[2,3,0,1] row_mask:0xf bank_mask:0xf
	v_mov_b32_dpp v245, v243 quad_perm:[2,3,0,1] row_mask:0xf bank_mask:0xf
	v_mov_b32_dpp v249, v247 quad_perm:[2,3,0,1] row_mask:0xf bank_mask:0xf
	v_mov_b32_dpp v253, v251 quad_perm:[2,3,0,1] row_mask:0xf bank_mask:0xf
	v_cndmask_b32_e64 v223, v225, v224, s[98:99]
	v_cndmask_b32_e64 v227, v229, v228, s[98:99]
	v_cndmask_b32_e64 v231, v233, v232, s[98:99]
	v_cndmask_b32_e64 v235, v237, v236, s[98:99]
	v_cndmask_b32_e64 v239, v241, v240, s[98:99]
	v_cndmask_b32_e64 v243, v245, v244, s[98:99]
	v_cndmask_b32_e64 v247, v249, v248, s[98:99]
	v_cndmask_b32_e64 v251, v253, v252, s[98:99]
	v_cndmask_b32_e64 v222, v222, v225, s[98:99]
	v_cndmask_b32_e64 v226, v226, v229, s[98:99]
	v_cndmask_b32_e64 v230, v230, v233, s[98:99]
	v_cndmask_b32_e64 v234, v234, v237, s[98:99]
	v_cndmask_b32_e64 v238, v238, v241, s[98:99]
	v_cndmask_b32_e64 v242, v242, v245, s[98:99]
	v_cndmask_b32_e64 v246, v246, v249, s[98:99]
	v_cndmask_b32_e64 v250, v250, v253, s[98:99]
	global_store_dwordx2 v[202:203], v[222:223], off offset:2048
	global_store_dwordx2 v[202:203], v[226:227], off offset:2112
	global_store_dwordx2 v[202:203], v[230:231], off offset:2176
	global_store_dwordx2 v[202:203], v[234:235], off offset:2240
	global_store_dwordx2 v[202:203], v[238:239], off offset:2304
	global_store_dwordx2 v[202:203], v[242:243], off offset:2368
	global_store_dwordx2 v[202:203], v[246:247], off offset:2432
	global_store_dwordx2 v[202:203], v[250:251], off offset:2496
	v_lshl_add_u64 v[202:203], v[202:203], 0, s[100:101]
	v_lshl_add_u64 v[32:33], v[32:33], 0, s[22:23]
	v_add_u32_e32 v17, 0x4000, v13
	ds_read2_b32 v[46:47], v17 offset1:32
	ds_read2_b32 v[48:49], v17 offset0:64 offset1:96
	v_mov_b32_e32 v64, v194
	v_mov_b32_e32 v65, v196
	v_mov_b32_e32 v75, v197
	v_mov_b32_e32 v76, v198
	v_mov_b32_e32 v77, v199
	v_mov_b32_e32 v78, v200
	s_waitcnt lgkmcnt(0)
	v_sub_f32_e32 v31, v88, v46
	v_sub_f32_e32 v60, v87, v47
	ds_read2_b32 v[46:47], v17 offset0:128 offset1:160
	v_mul_f32_e32 v61, v60, v60
	v_sub_f32_e32 v62, v86, v48
	v_sub_f32_e32 v63, v85, v49
	ds_read2_b32 v[48:49], v17 offset0:192 offset1:224
	v_fmac_f32_e32 v61, v31, v31
	v_fmac_f32_e32 v61, v62, v62
	v_fmac_f32_e32 v61, v63, v63
	s_waitcnt lgkmcnt(0)
	v_sub_f32_e32 v46, v84, v46
	v_fmac_f32_e32 v61, v46, v46
	v_sub_f32_e32 v17, v83, v47
	v_fmac_f32_e32 v61, v17, v17
	v_sub_f32_e32 v48, v82, v48
	v_fmac_f32_e32 v61, v48, v48
	v_sub_f32_e32 v49, v74, v49
	v_fmac_f32_e32 v61, v49, v49
	s_nop 1
	v_mov_b32_dpp v74, v61 quad_perm:[1,0,3,2] row_mask:0xf bank_mask:0xf
	v_mov_b32_e32 v47, v195
	s_waitcnt lgkmcnt(0)
	v_add_f32_e32 v61, v61, v74
	s_nop 1
	v_mov_b32_dpp v74, v61 quad_perm:[2,3,0,1] row_mask:0xf bank_mask:0xf
	s_waitcnt lgkmcnt(0)
	v_add_f32_e32 v61, v61, v74
	s_nop 1
	v_mov_b32_dpp v74, v61 row_half_mirror row_mask:0xf bank_mask:0xf
	s_waitcnt lgkmcnt(0)
	v_add_f32_e32 v61, v61, v74
	s_nop 1
	v_mov_b32_dpp v74, v61 row_mirror row_mask:0xf bank_mask:0xf
	s_waitcnt lgkmcnt(0)
	v_add_f32_e32 v61, v61, v74
	v_mov_b32_e32 v74, v201
	v_mov_b32_e32 v79, v61
	s_nop 1
	v_permlane16_swap_b32_e32 v79, v61
	s_waitcnt lgkmcnt(0)
	v_add_f32_e32 v61, v61, v79
	v_fmamk_f32 v61, v61, 0x3b800000, v190
	v_mul_f32_e32 v79, 0x4f800000, v61
	v_cmp_gt_f32_e32 vcc, s56, v61
	s_nop 1
	v_cndmask_b32_e32 v61, v61, v79, vcc
	v_sqrt_f32_e32 v79, v61
	s_nop 0
	v_add_u32_e32 v80, -1, v79
	v_fma_f32 v81, -v80, v79, v61
	v_cmp_ge_f32_e64 s[0:1], 0, v81
	v_add_u32_e32 v81, 1, v79
	s_nop 0
	v_cndmask_b32_e64 v80, v79, v80, s[0:1]
	v_fma_f32 v79, -v81, v79, v61
	v_cmp_lt_f32_e64 s[0:1], 0, v79
	s_nop 1
	v_cndmask_b32_e64 v79, v80, v81, s[0:1]
	v_mul_f32_e32 v80, 0x37800000, v79
	v_cndmask_b32_e32 v79, v79, v80, vcc
	v_cmp_class_f32_e32 vcc, v61, v189
	s_nop 1
	v_cndmask_b32_e32 v61, v79, v61, vcc
	v_div_scale_f32 v79, s[0:1], v61, v61, s87
	v_rcp_f32_e32 v80, v79
	s_nop 0
	v_fma_f32 v81, -v79, v80, 1.0
	v_fmac_f32_e32 v80, v81, v80
	v_div_scale_f32 v81, vcc, s87, v61, s87
	v_mul_f32_e32 v82, v81, v80
	v_fma_f32 v83, -v79, v82, v81
	v_fmac_f32_e32 v82, v83, v80
	v_fma_f32 v79, -v79, v82, v81
	v_div_fmas_f32 v79, v79, v80, v82
	v_div_fixup_f32 v61, v79, v61, s87
	v_mul_f32_e32 v31, v31, v61
	v_mul_f32_e32 v31, v64, v31
	v_mov_b32_e32 v222, v31
	v_mul_f32_e32 v31, v60, v61
	v_mul_f32_e32 v17, v17, v61
	v_mul_f32_e32 v31, v47, v31
	v_mov_b32_e32 v226, v31
	v_mul_f32_e32 v31, v62, v61
	v_mul_f32_e32 v31, v65, v31
	v_mov_b32_e32 v230, v31
	v_mul_f32_e32 v31, v63, v61
	v_mul_f32_e32 v31, v75, v31
	v_mov_b32_e32 v234, v31
	v_mul_f32_e32 v31, v46, v61
	v_mul_f32_e32 v31, v76, v31
	v_mov_b32_e32 v238, v31
	v_mul_f32_e32 v17, v17, v77
	v_mov_b32_e32 v242, v17
	v_mul_f32_e32 v17, v48, v61
	v_mul_f32_e32 v17, v17, v78
	v_mov_b32_e32 v246, v17
	v_mul_f32_e32 v17, v49, v61
	v_mul_f32_e32 v17, v17, v74
	v_mov_b32_e32 v250, v17
	v_lshl_add_u64 v[32:33], v[32:33], 0, s[20:21]
	v_add_u32_e32 v17, 0x4400, v13
	ds_read2_b32 v[46:47], v17 offset1:32
	ds_read2_b32 v[48:49], v17 offset0:64 offset1:96
	v_mov_b32_e32 v64, v194
	v_mov_b32_e32 v65, v196
	s_waitcnt lgkmcnt(0)
	v_sub_f32_e32 v31, v73, v46
	v_sub_f32_e32 v60, v72, v47
	ds_read2_b32 v[46:47], v17 offset0:128 offset1:160
	v_mul_f32_e32 v61, v60, v60
	v_sub_f32_e32 v62, v71, v48
	v_sub_f32_e32 v63, v70, v49
	ds_read2_b32 v[48:49], v17 offset0:192 offset1:224
	v_fmac_f32_e32 v61, v31, v31
	v_fmac_f32_e32 v61, v62, v62
	v_fmac_f32_e32 v61, v63, v63
	s_waitcnt lgkmcnt(0)
; __device__ __forceinline__ bf16_t f2bf(float f) { unsigned u = __float_as_uint(f); u += 0x7FFFu + ((u >> 16) & 1u); return (bf16_t)(u >> 16); }
; __device__ __forceinline__ void df_unit(LAS unsigned char* lds, const bf16_t* qkv, bf16_t* attout, const float* subg, int b_, int h_, int qb_, int wid, int) {
;     ...
;         for (int r = 0; r < 16; ++r) { const int rowc = (r & 3) + 8 * (r >> 2); float ss = 0.f;
; #pragma unroll
;             for (int d = 0; d < 8; ++d) { o[d][r] -= xr[rowc * 256 + d * 32]; ss += o[d][r] * o[d][r]; }
;             ss += __shfl_xor(ss, 1); ss += __shfl_xor(ss, 2); ss += __shfl_xor(ss, 4); ss += __shfl_xor(ss, 8); ss += __shfl_xor(ss, 16);
;             const float rstd = (1.0f - LAMBDA_INIT) / sqrtf(ss * (1.0f / 256.0f) + SUBLN_EPS);
; #pragma unroll
;             for (int d = 0; d < 8; ++d) op[d * 32] = f2bf(o[d][r] * rstd * subg[d * 32 + r32]);
;             op += ((r & 3) == 3 ? 5 : 1) * DM; asm volatile("" : "+v"(op) :: "memory"); } }
	v_sub_f32_e32 v46, v69, v46
	v_fmac_f32_e32 v61, v46, v46
	v_sub_f32_e32 v17, v68, v47
	v_fmac_f32_e32 v61, v17, v17
	v_sub_f32_e32 v48, v67, v48
	v_fmac_f32_e32 v61, v48, v48
	v_sub_f32_e32 v49, v66, v49
	v_fmac_f32_e32 v61, v49, v49
	s_nop 1
	v_mov_b32_dpp v66, v61 quad_perm:[1,0,3,2] row_mask:0xf bank_mask:0xf
	v_mov_b32_e32 v47, v195
	v_mov_b32_e32 v67, v197
	v_mov_b32_e32 v68, v198
	v_mov_b32_e32 v69, v199
	v_mov_b32_e32 v70, v200
	s_waitcnt lgkmcnt(0)
	v_add_f32_e32 v61, v61, v66
	s_nop 1
	v_mov_b32_dpp v66, v61 quad_perm:[2,3,0,1] row_mask:0xf bank_mask:0xf
	s_waitcnt lgkmcnt(0)
	v_add_f32_e32 v61, v61, v66
	s_nop 1
	v_mov_b32_dpp v66, v61 row_half_mirror row_mask:0xf bank_mask:0xf
	s_waitcnt lgkmcnt(0)
	v_add_f32_e32 v61, v61, v66
	s_nop 1
	v_mov_b32_dpp v66, v61 row_mirror row_mask:0xf bank_mask:0xf
	s_waitcnt lgkmcnt(0)
	v_add_f32_e32 v61, v61, v66
	v_mov_b32_e32 v66, v201
	v_mov_b32_e32 v71, v61
	s_nop 1
	v_permlane16_swap_b32_e32 v71, v61
	s_waitcnt lgkmcnt(0)
	v_add_f32_e32 v61, v61, v71
	v_fmamk_f32 v61, v61, 0x3b800000, v190
	v_mul_f32_e32 v71, 0x4f800000, v61
	v_cmp_gt_f32_e32 vcc, s56, v61
	s_nop 1
	v_cndmask_b32_e32 v61, v61, v71, vcc
	v_sqrt_f32_e32 v71, v61
	s_nop 0
	v_add_u32_e32 v72, -1, v71
	v_fma_f32 v73, -v72, v71, v61
	v_cmp_ge_f32_e64 s[0:1], 0, v73
	v_add_u32_e32 v73, 1, v71
	s_nop 0
	v_cndmask_b32_e64 v72, v71, v72, s[0:1]
	v_fma_f32 v71, -v73, v71, v61
	v_cmp_lt_f32_e64 s[0:1], 0, v71
	s_nop 1
	v_cndmask_b32_e64 v71, v72, v73, s[0:1]
	v_mul_f32_e32 v72, 0x37800000, v71
	v_cndmask_b32_e32 v71, v71, v72, vcc
	v_cmp_class_f32_e32 vcc, v61, v189
	s_nop 1
	v_cndmask_b32_e32 v61, v71, v61, vcc
	v_div_scale_f32 v71, s[0:1], v61, v61, s87
	v_rcp_f32_e32 v72, v71
	s_nop 0
	v_fma_f32 v73, -v71, v72, 1.0
	v_fmac_f32_e32 v72, v73, v72
	v_div_scale_f32 v73, vcc, s87, v61, s87
	v_mul_f32_e32 v74, v73, v72
	v_fma_f32 v75, -v71, v74, v73
	v_fmac_f32_e32 v74, v75, v72
	v_fma_f32 v71, -v71, v74, v73
	v_div_fmas_f32 v71, v71, v72, v74
	v_div_fixup_f32 v61, v71, v61, s87
	v_mul_f32_e32 v31, v31, v61
	v_mul_f32_e32 v31, v64, v31
	v_mov_b32_e32 v223, v31
	v_mul_f32_e32 v31, v60, v61
	v_mul_f32_e32 v31, v47, v31
	v_mov_b32_e32 v227, v31
	v_mul_f32_e32 v31, v62, v61
	v_mul_f32_e32 v31, v65, v31
	v_mov_b32_e32 v231, v31
	v_mul_f32_e32 v31, v63, v61
	v_mul_f32_e32 v31, v67, v31
	v_mov_b32_e32 v235, v31
	v_mul_f32_e32 v31, v46, v61
	v_mul_f32_e32 v31, v68, v31
	v_mul_f32_e32 v17, v17, v61
	v_mov_b32_e32 v239, v31
	v_mul_f32_e32 v17, v17, v69
	v_mov_b32_e32 v243, v17
	v_mul_f32_e32 v17, v48, v61
	v_mul_f32_e32 v17, v17, v70
	v_mov_b32_e32 v247, v17
	v_mul_f32_e32 v17, v49, v61
	v_mul_f32_e32 v17, v17, v66
	v_mov_b32_e32 v251, v17
	v_lshl_add_u64 v[32:33], v[32:33], 0, s[20:21]
	v_add_u32_e32 v17, 0x4800, v13
	ds_read2_b32 v[46:47], v17 offset1:32
	ds_read2_b32 v[48:49], v17 offset0:64 offset1:96
	v_mov_b32_e32 v60, v198
	v_mov_b32_e32 v61, v199
	v_mov_b32_e32 v62, v200
	s_waitcnt lgkmcnt(0)
	v_sub_f32_e32 v31, v59, v46
	v_sub_f32_e32 v58, v58, v47
	ds_read2_b32 v[46:47], v17 offset0:128 offset1:160
	v_mul_f32_e32 v59, v58, v58
	v_sub_f32_e32 v57, v57, v48
	v_sub_f32_e32 v56, v56, v49
	ds_read2_b32 v[48:49], v17 offset0:192 offset1:224
	v_fmac_f32_e32 v59, v31, v31
	v_fmac_f32_e32 v59, v57, v57
	v_fmac_f32_e32 v59, v56, v56
	s_waitcnt lgkmcnt(0)
	v_sub_f32_e32 v46, v55, v46
	v_fmac_f32_e32 v59, v46, v46
	v_sub_f32_e32 v17, v54, v47
	v_mov_b32_e32 v55, v194
	v_mov_b32_e32 v47, v195
	v_mov_b32_e32 v54, v197
	v_fmac_f32_e32 v59, v17, v17
	v_sub_f32_e32 v48, v53, v48
	v_fmac_f32_e32 v59, v48, v48
	v_sub_f32_e32 v49, v52, v49
	v_fmac_f32_e32 v59, v49, v49
	s_nop 1
	v_mov_b32_dpp v53, v59 quad_perm:[1,0,3,2] row_mask:0xf bank_mask:0xf
	v_mov_b32_e32 v52, v196
	s_waitcnt lgkmcnt(0)
	v_add_f32_e32 v53, v59, v53
	s_nop 1
	v_mov_b32_dpp v59, v53 quad_perm:[2,3,0,1] row_mask:0xf bank_mask:0xf
	s_waitcnt lgkmcnt(0)
	v_add_f32_e32 v53, v53, v59
	s_nop 1
	v_mov_b32_dpp v59, v53 row_half_mirror row_mask:0xf bank_mask:0xf
	s_waitcnt lgkmcnt(0)
	v_add_f32_e32 v53, v53, v59
	s_nop 1
	v_mov_b32_dpp v59, v53 row_mirror row_mask:0xf bank_mask:0xf
	s_waitcnt lgkmcnt(0)
	v_add_f32_e32 v53, v53, v59
	v_mov_b32_e32 v59, v201
	v_mov_b32_e32 v63, v53
	s_nop 1
	v_permlane16_swap_b32_e32 v63, v53
	s_waitcnt lgkmcnt(0)
	v_add_f32_e32 v53, v53, v63
	v_fmamk_f32 v53, v53, 0x3b800000, v190
	v_mul_f32_e32 v63, 0x4f800000, v53
	v_cmp_gt_f32_e32 vcc, s56, v53
	s_nop 1
	v_cndmask_b32_e32 v53, v53, v63, vcc
	v_sqrt_f32_e32 v63, v53
	s_nop 0
	v_add_u32_e32 v64, -1, v63
	v_fma_f32 v65, -v64, v63, v53
	v_cmp_ge_f32_e64 s[0:1], 0, v65
	v_add_u32_e32 v65, 1, v63
	s_nop 0
	v_cndmask_b32_e64 v64, v63, v64, s[0:1]
	v_fma_f32 v63, -v65, v63, v53
	v_cmp_lt_f32_e64 s[0:1], 0, v63
	s_nop 1
	v_cndmask_b32_e64 v63, v64, v65, s[0:1]
	v_mul_f32_e32 v64, 0x37800000, v63
	v_cndmask_b32_e32 v63, v63, v64, vcc
	v_cmp_class_f32_e32 vcc, v53, v189
	s_nop 1
	v_cndmask_b32_e32 v53, v63, v53, vcc
	v_div_scale_f32 v63, s[0:1], v53, v53, s87
	v_rcp_f32_e32 v64, v63
	s_nop 0
	v_fma_f32 v65, -v63, v64, 1.0
	v_fmac_f32_e32 v64, v65, v64
	v_div_scale_f32 v65, vcc, s87, v53, s87
	v_mul_f32_e32 v66, v65, v64
	v_fma_f32 v67, -v63, v66, v65
	v_fmac_f32_e32 v66, v67, v64
	v_fma_f32 v63, -v63, v66, v65
	v_div_fmas_f32 v63, v63, v64, v66
	v_div_fixup_f32 v53, v63, v53, s87
	v_mul_f32_e32 v31, v31, v53
	v_mul_f32_e32 v31, v55, v31
	v_mov_b32_e32 v224, v31
	v_mul_f32_e32 v31, v58, v53
	v_mul_f32_e32 v31, v47, v31
	v_mov_b32_e32 v228, v31
	v_mul_f32_e32 v31, v57, v53
	v_mul_f32_e32 v31, v52, v31
	v_mov_b32_e32 v232, v31
	v_mul_f32_e32 v31, v56, v53
	v_mul_f32_e32 v31, v54, v31
	v_mov_b32_e32 v236, v31
	v_mul_f32_e32 v31, v46, v53
	v_mul_f32_e32 v31, v60, v31
	v_mul_f32_e32 v17, v17, v53
	v_mov_b32_e32 v240, v31
	v_mul_f32_e32 v17, v17, v61
	v_mov_b32_e32 v244, v17
	v_mul_f32_e32 v17, v48, v53
	v_mul_f32_e32 v17, v17, v62
	v_mov_b32_e32 v248, v17
	v_mul_f32_e32 v17, v49, v53
	v_mul_f32_e32 v17, v17, v59
	v_mov_b32_e32 v252, v17
	v_lshl_add_u64 v[32:33], v[32:33], 0, s[20:21]
	v_add_u32_e32 v17, 0x4c00, v13
	ds_read2_b32 v[46:47], v17 offset1:32
	ds_read2_b32 v[48:49], v17 offset0:64 offset1:96
	v_mov_b32_e32 v52, v198
	v_mov_b32_e32 v53, v199
	v_mov_b32_e32 v54, v200
	s_waitcnt lgkmcnt(0)
; __device__ __forceinline__ bf16_t f2bf(float f) { unsigned u = __float_as_uint(f); u += 0x7FFFu + ((u >> 16) & 1u); return (bf16_t)(u >> 16); }
; __device__ __forceinline__ void df_unit(LAS unsigned char* lds, const bf16_t* qkv, bf16_t* attout, const float* subg, int b_, int h_, int qb_, int wid, int) {
;     ...
;         for (int r = 0; r < 16; ++r) { const int rowc = (r & 3) + 8 * (r >> 2); float ss = 0.f;
; #pragma unroll
;             for (int d = 0; d < 8; ++d) { o[d][r] -= xr[rowc * 256 + d * 32]; ss += o[d][r] * o[d][r]; }
;             ss += __shfl_xor(ss, 1); ss += __shfl_xor(ss, 2); ss += __shfl_xor(ss, 4); ss += __shfl_xor(ss, 8); ss += __shfl_xor(ss, 16);
;             const float rstd = (1.0f - LAMBDA_INIT) / sqrtf(ss * (1.0f / 256.0f) + SUBLN_EPS);
; #pragma unroll
;             for (int d = 0; d < 8; ++d) op[d * 32] = f2bf(o[d][r] * rstd * subg[d * 32 + r32]);
;             op += ((r & 3) == 3 ? 5 : 1) * DM; asm volatile("" : "+v"(op) :: "memory"); } }
	v_sub_f32_e32 v31, v51, v46
	v_sub_f32_e32 v50, v50, v47
	ds_read2_b32 v[46:47], v17 offset0:128 offset1:160
	v_mul_f32_e32 v51, v50, v50
	v_sub_f32_e32 v48, v45, v48
	v_sub_f32_e32 v49, v44, v49
	ds_read2_b32 v[44:45], v17 offset0:192 offset1:224
	v_fmac_f32_e32 v51, v31, v31
	v_fmac_f32_e32 v51, v48, v48
	v_fmac_f32_e32 v51, v49, v49
	s_waitcnt lgkmcnt(0)
	v_sub_f32_e32 v43, v43, v46
	v_fmac_f32_e32 v51, v43, v43
	v_sub_f32_e32 v17, v42, v47
	v_mov_b32_e32 v46, v194
	v_mov_b32_e32 v42, v195
	v_mov_b32_e32 v47, v197
	v_fmac_f32_e32 v51, v17, v17
	v_sub_f32_e32 v41, v41, v44
	v_fmac_f32_e32 v51, v41, v41
	v_sub_f32_e32 v40, v40, v45
	v_fmac_f32_e32 v51, v40, v40
	s_nop 1
	v_mov_b32_dpp v45, v51 quad_perm:[1,0,3,2] row_mask:0xf bank_mask:0xf
	v_mov_b32_e32 v44, v196
	s_waitcnt lgkmcnt(0)
	v_add_f32_e32 v45, v51, v45
	s_nop 1
	v_mov_b32_dpp v51, v45 quad_perm:[2,3,0,1] row_mask:0xf bank_mask:0xf
	s_waitcnt lgkmcnt(0)
	v_add_f32_e32 v45, v45, v51
	s_nop 1
	v_mov_b32_dpp v51, v45 row_half_mirror row_mask:0xf bank_mask:0xf
	s_waitcnt lgkmcnt(0)
	v_add_f32_e32 v45, v45, v51
	s_nop 1
	v_mov_b32_dpp v51, v45 row_mirror row_mask:0xf bank_mask:0xf
	s_waitcnt lgkmcnt(0)
	v_add_f32_e32 v45, v45, v51
	v_mov_b32_e32 v51, v201
	v_mov_b32_e32 v55, v45
	s_nop 1
	v_permlane16_swap_b32_e32 v55, v45
	s_waitcnt lgkmcnt(0)
	v_add_f32_e32 v45, v45, v55
	v_fmamk_f32 v45, v45, 0x3b800000, v190
	v_mul_f32_e32 v55, 0x4f800000, v45
	v_cmp_gt_f32_e32 vcc, s56, v45
	s_nop 1
	v_cndmask_b32_e32 v45, v45, v55, vcc
	v_sqrt_f32_e32 v55, v45
	s_nop 0
	v_add_u32_e32 v56, -1, v55
	v_fma_f32 v57, -v56, v55, v45
	v_cmp_ge_f32_e64 s[0:1], 0, v57
	v_add_u32_e32 v57, 1, v55
	s_nop 0
	v_cndmask_b32_e64 v56, v55, v56, s[0:1]
	v_fma_f32 v55, -v57, v55, v45
	v_cmp_lt_f32_e64 s[0:1], 0, v55
	s_nop 1
	v_cndmask_b32_e64 v55, v56, v57, s[0:1]
	v_mul_f32_e32 v56, 0x37800000, v55
	v_cndmask_b32_e32 v55, v55, v56, vcc
	v_cmp_class_f32_e32 vcc, v45, v189
	s_nop 1
	v_cndmask_b32_e32 v45, v55, v45, vcc
	v_div_scale_f32 v55, s[0:1], v45, v45, s87
	v_rcp_f32_e32 v56, v55
	s_nop 0
	v_fma_f32 v57, -v55, v56, 1.0
	v_fmac_f32_e32 v56, v57, v56
	v_div_scale_f32 v57, vcc, s87, v45, s87
	v_mul_f32_e32 v58, v57, v56
	v_fma_f32 v59, -v55, v58, v57
	v_fmac_f32_e32 v58, v59, v56
	v_fma_f32 v55, -v55, v58, v57
	v_div_fmas_f32 v55, v55, v56, v58
	v_div_fixup_f32 v45, v55, v45, s87
	v_mul_f32_e32 v31, v31, v45
	v_mul_f32_e32 v31, v46, v31
	v_mov_b32_e32 v225, v31
	v_mul_f32_e32 v31, v50, v45
	v_mul_f32_e32 v31, v42, v31
	v_mov_b32_e32 v229, v31
	v_mul_f32_e32 v31, v48, v45
	v_mul_f32_e32 v31, v44, v31
	v_mov_b32_e32 v233, v31
	v_mul_f32_e32 v31, v49, v45
	v_mul_f32_e32 v31, v47, v31
	v_mov_b32_e32 v237, v31
	v_mul_f32_e32 v31, v43, v45
	v_mul_f32_e32 v31, v52, v31
	v_mul_f32_e32 v17, v17, v45
	v_mov_b32_e32 v241, v31
	v_mul_f32_e32 v17, v17, v53
	v_mov_b32_e32 v245, v17
	v_mul_f32_e32 v17, v41, v45
	v_mul_f32_e32 v17, v17, v54
	v_mov_b32_e32 v249, v17
	v_mul_f32_e32 v17, v40, v45
	v_mul_f32_e32 v17, v17, v51
	v_mov_b32_e32 v253, v17
	v_cvt_pk_bf16_f32 v222, v222, v223
	v_cvt_pk_bf16_f32 v226, v226, v227
	v_cvt_pk_bf16_f32 v230, v230, v231
	v_cvt_pk_bf16_f32 v234, v234, v235
	v_cvt_pk_bf16_f32 v238, v238, v239
	v_cvt_pk_bf16_f32 v242, v242, v243
	v_cvt_pk_bf16_f32 v246, v246, v247
	v_cvt_pk_bf16_f32 v250, v250, v251
	v_cvt_pk_bf16_f32 v224, v224, v225
	v_cvt_pk_bf16_f32 v228, v228, v229
	v_cvt_pk_bf16_f32 v232, v232, v233
	v_cvt_pk_bf16_f32 v236, v236, v237
	v_cvt_pk_bf16_f32 v240, v240, v241
	v_cvt_pk_bf16_f32 v244, v244, v245
	v_cvt_pk_bf16_f32 v248, v248, v249
	v_cvt_pk_bf16_f32 v252, v252, v253
	v_mov_b32_dpp v223, v222 quad_perm:[1,0,3,2] row_mask:0xf bank_mask:0xf
	v_mov_b32_dpp v227, v226 quad_perm:[1,0,3,2] row_mask:0xf bank_mask:0xf
	v_mov_b32_dpp v231, v230 quad_perm:[1,0,3,2] row_mask:0xf bank_mask:0xf
	v_mov_b32_dpp v235, v234 quad_perm:[1,0,3,2] row_mask:0xf bank_mask:0xf
	v_mov_b32_dpp v239, v238 quad_perm:[1,0,3,2] row_mask:0xf bank_mask:0xf
	v_mov_b32_dpp v243, v242 quad_perm:[1,0,3,2] row_mask:0xf bank_mask:0xf
	v_mov_b32_dpp v247, v246 quad_perm:[1,0,3,2] row_mask:0xf bank_mask:0xf
	v_mov_b32_dpp v251, v250 quad_perm:[1,0,3,2] row_mask:0xf bank_mask:0xf
	v_mov_b32_dpp v225, v224 quad_perm:[1,0,3,2] row_mask:0xf bank_mask:0xf
	v_mov_b32_dpp v229, v228 quad_perm:[1,0,3,2] row_mask:0xf bank_mask:0xf
	v_mov_b32_dpp v233, v232 quad_perm:[1,0,3,2] row_mask:0xf bank_mask:0xf
	v_mov_b32_dpp v237, v236 quad_perm:[1,0,3,2] row_mask:0xf bank_mask:0xf
	v_mov_b32_dpp v241, v240 quad_perm:[1,0,3,2] row_mask:0xf bank_mask:0xf
	v_mov_b32_dpp v245, v244 quad_perm:[1,0,3,2] row_mask:0xf bank_mask:0xf
	v_mov_b32_dpp v249, v248 quad_perm:[1,0,3,2] row_mask:0xf bank_mask:0xf
	v_mov_b32_dpp v253, v252 quad_perm:[1,0,3,2] row_mask:0xf bank_mask:0xf
	v_perm_b32 v222, v222, v223, v204
	v_perm_b32 v226, v226, v227, v204
	v_perm_b32 v230, v230, v231, v204
	v_perm_b32 v234, v234, v235, v204
	v_perm_b32 v238, v238, v239, v204
	v_perm_b32 v242, v242, v243, v204
	v_perm_b32 v246, v246, v247, v204
	v_perm_b32 v250, v250, v251, v204
	v_perm_b32 v224, v224, v225, v204
	v_perm_b32 v228, v228, v229, v204
	v_perm_b32 v232, v232, v233, v204
	v_perm_b32 v236, v236, v237, v204
	v_perm_b32 v240, v240, v241, v204
	v_perm_b32 v244, v244, v245, v204
	v_perm_b32 v248, v248, v249, v204
	v_perm_b32 v252, v252, v253, v204
	v_cndmask_b32_e64 v223, v224, v222, s[98:99]
	v_cndmask_b32_e64 v227, v228, v226, s[98:99]
	v_cndmask_b32_e64 v231, v232, v230, s[98:99]
	v_cndmask_b32_e64 v235, v236, v234, s[98:99]
	v_cndmask_b32_e64 v239, v240, v238, s[98:99]
	v_cndmask_b32_e64 v243, v244, v242, s[98:99]
	v_cndmask_b32_e64 v247, v248, v246, s[98:99]
; __device__ __forceinline__ bf16_t f2bf(float f) { unsigned u = __float_as_uint(f); u += 0x7FFFu + ((u >> 16) & 1u); return (bf16_t)(u >> 16); }
; __device__ __forceinline__ void df_unit(LAS unsigned char* lds, const bf16_t* qkv, bf16_t* attout, const float* subg, int b_, int h_, int qb_, int wid, int) {
;     ...
;         for (int r = 0; r < 16; ++r) { const int rowc = (r & 3) + 8 * (r >> 2); float ss = 0.f;
; #pragma unroll
;             for (int d = 0; d < 8; ++d) { o[d][r] -= xr[rowc * 256 + d * 32]; ss += o[d][r] * o[d][r]; }
;             ss += __shfl_xor(ss, 1); ss += __shfl_xor(ss, 2); ss += __shfl_xor(ss, 4); ss += __shfl_xor(ss, 8); ss += __shfl_xor(ss, 16);
;             const float rstd = (1.0f - LAMBDA_INIT) / sqrtf(ss * (1.0f / 256.0f) + SUBLN_EPS);
; #pragma unroll
;             for (int d = 0; d < 8; ++d) op[d * 32] = f2bf(o[d][r] * rstd * subg[d * 32 + r32]);
;             op += ((r & 3) == 3 ? 5 : 1) * DM; asm volatile("" : "+v"(op) :: "memory"); } }
	v_cndmask_b32_e64 v251, v252, v250, s[98:99]
	v_mov_b32_dpp v225, v223 quad_perm:[2,3,0,1] row_mask:0xf bank_mask:0xf
	v_mov_b32_dpp v229, v227 quad_perm:[2,3,0,1] row_mask:0xf bank_mask:0xf
	v_mov_b32_dpp v233, v231 quad_perm:[2,3,0,1] row_mask:0xf bank_mask:0xf
	v_mov_b32_dpp v237, v235 quad_perm:[2,3,0,1] row_mask:0xf bank_mask:0xf
	v_mov_b32_dpp v241, v239 quad_perm:[2,3,0,1] row_mask:0xf bank_mask:0xf
	v_mov_b32_dpp v245, v243 quad_perm:[2,3,0,1] row_mask:0xf bank_mask:0xf
	v_mov_b32_dpp v249, v247 quad_perm:[2,3,0,1] row_mask:0xf bank_mask:0xf
	v_mov_b32_dpp v253, v251 quad_perm:[2,3,0,1] row_mask:0xf bank_mask:0xf
	v_cndmask_b32_e64 v223, v225, v224, s[98:99]
	v_cndmask_b32_e64 v227, v229, v228, s[98:99]
	v_cndmask_b32_e64 v231, v233, v232, s[98:99]
	v_cndmask_b32_e64 v235, v237, v236, s[98:99]
	v_cndmask_b32_e64 v239, v241, v240, s[98:99]
	v_cndmask_b32_e64 v243, v245, v244, s[98:99]
	v_cndmask_b32_e64 v247, v249, v248, s[98:99]
	v_cndmask_b32_e64 v251, v253, v252, s[98:99]
	v_cndmask_b32_e64 v222, v222, v225, s[98:99]
	v_cndmask_b32_e64 v226, v226, v229, s[98:99]
	v_cndmask_b32_e64 v230, v230, v233, s[98:99]
	v_cndmask_b32_e64 v234, v234, v237, s[98:99]
	v_cndmask_b32_e64 v238, v238, v241, s[98:99]
	v_cndmask_b32_e64 v242, v242, v245, s[98:99]
	v_cndmask_b32_e64 v246, v246, v249, s[98:99]
	v_cndmask_b32_e64 v250, v250, v253, s[98:99]
	global_store_dwordx2 v[202:203], v[222:223], off offset:2048
	global_store_dwordx2 v[202:203], v[226:227], off offset:2112
	global_store_dwordx2 v[202:203], v[230:231], off offset:2176
	global_store_dwordx2 v[202:203], v[234:235], off offset:2240
	global_store_dwordx2 v[202:203], v[238:239], off offset:2304
	global_store_dwordx2 v[202:203], v[242:243], off offset:2368
	global_store_dwordx2 v[202:203], v[246:247], off offset:2432
	global_store_dwordx2 v[202:203], v[250:251], off offset:2496
	v_lshl_add_u64 v[202:203], v[202:203], 0, s[100:101]
	v_lshl_add_u64 v[32:33], v[32:33], 0, s[22:23]
	v_add_u32_e32 v17, 0x6000, v13
	ds_read2_b32 v[40:41], v17 offset1:32
	ds_read2_b32 v[42:43], v17 offset0:64 offset1:96
	v_mov_b32_e32 v44, v198
	v_mov_b32_e32 v45, v199
	v_mov_b32_e32 v46, v200
	s_waitcnt lgkmcnt(0)
	v_sub_f32_e32 v31, v39, v40
	v_sub_f32_e32 v40, v38, v41
	ds_read2_b32 v[38:39], v17 offset0:128 offset1:160
	v_mul_f32_e32 v41, v40, v40
	v_sub_f32_e32 v42, v37, v42
	v_sub_f32_e32 v43, v36, v43
	ds_read2_b32 v[36:37], v17 offset0:192 offset1:224
	v_fmac_f32_e32 v41, v31, v31
	v_fmac_f32_e32 v41, v42, v42
	v_fmac_f32_e32 v41, v43, v43
	s_waitcnt lgkmcnt(0)
	v_sub_f32_e32 v35, v35, v38
	v_fmac_f32_e32 v41, v35, v35
	v_sub_f32_e32 v17, v34, v39
	v_mov_b32_e32 v38, v194
	v_mov_b32_e32 v34, v195
	v_mov_b32_e32 v39, v197
	v_fmac_f32_e32 v41, v17, v17
	v_sub_f32_e32 v30, v30, v36
	v_fmac_f32_e32 v41, v30, v30
	v_sub_f32_e32 v29, v29, v37
	v_fmac_f32_e32 v41, v29, v29
	s_nop 1
	v_mov_b32_dpp v37, v41 quad_perm:[1,0,3,2] row_mask:0xf bank_mask:0xf
	v_mov_b32_e32 v36, v196
	s_waitcnt lgkmcnt(0)
	v_add_f32_e32 v37, v41, v37
	s_nop 1
	v_mov_b32_dpp v41, v37 quad_perm:[2,3,0,1] row_mask:0xf bank_mask:0xf
	s_waitcnt lgkmcnt(0)
	v_add_f32_e32 v37, v37, v41
	s_nop 1
	v_mov_b32_dpp v41, v37 row_half_mirror row_mask:0xf bank_mask:0xf
	s_waitcnt lgkmcnt(0)
	v_add_f32_e32 v37, v37, v41
	s_nop 1
	v_mov_b32_dpp v41, v37 row_mirror row_mask:0xf bank_mask:0xf
	s_waitcnt lgkmcnt(0)
	v_add_f32_e32 v37, v37, v41
	v_mov_b32_e32 v41, v201
	v_mov_b32_e32 v47, v37
	s_nop 1
	v_permlane16_swap_b32_e32 v47, v37
	s_waitcnt lgkmcnt(0)
	v_add_f32_e32 v37, v37, v47
	v_fmamk_f32 v37, v37, 0x3b800000, v190
	v_mul_f32_e32 v47, 0x4f800000, v37
	v_cmp_gt_f32_e32 vcc, s56, v37
	s_nop 1
	v_cndmask_b32_e32 v37, v37, v47, vcc
	v_sqrt_f32_e32 v47, v37
	s_nop 0
	v_add_u32_e32 v48, -1, v47
	v_fma_f32 v49, -v48, v47, v37
	v_cmp_ge_f32_e64 s[0:1], 0, v49
	v_add_u32_e32 v49, 1, v47
	s_nop 0
	v_cndmask_b32_e64 v48, v47, v48, s[0:1]
	v_fma_f32 v47, -v49, v47, v37
	v_cmp_lt_f32_e64 s[0:1], 0, v47
	s_nop 1
	v_cndmask_b32_e64 v47, v48, v49, s[0:1]
	v_mul_f32_e32 v48, 0x37800000, v47
	v_cndmask_b32_e32 v47, v47, v48, vcc
	v_cmp_class_f32_e32 vcc, v37, v189
	s_nop 1
	v_cndmask_b32_e32 v37, v47, v37, vcc
	v_div_scale_f32 v47, s[0:1], v37, v37, s87
	v_rcp_f32_e32 v48, v47
	s_nop 0
	v_fma_f32 v49, -v47, v48, 1.0
	v_fmac_f32_e32 v48, v49, v48
	v_div_scale_f32 v49, vcc, s87, v37, s87
	v_mul_f32_e32 v50, v49, v48
	v_fma_f32 v51, -v47, v50, v49
	v_fmac_f32_e32 v50, v51, v48
	v_fma_f32 v47, -v47, v50, v49
	v_div_fmas_f32 v47, v47, v48, v50
	v_div_fixup_f32 v37, v47, v37, s87
	v_mul_f32_e32 v31, v31, v37
	v_mul_f32_e32 v31, v38, v31
	v_mov_b32_e32 v222, v31
	v_mul_f32_e32 v31, v40, v37
	v_mul_f32_e32 v31, v34, v31
	v_mov_b32_e32 v226, v31
	v_mul_f32_e32 v31, v42, v37
	v_mul_f32_e32 v31, v36, v31
	v_mov_b32_e32 v230, v31
	v_mul_f32_e32 v31, v43, v37
	v_mul_f32_e32 v31, v39, v31
	v_mov_b32_e32 v234, v31
	v_mul_f32_e32 v31, v35, v37
	v_mul_f32_e32 v31, v44, v31
	v_mul_f32_e32 v17, v17, v37
	v_mov_b32_e32 v238, v31
	v_mul_f32_e32 v17, v17, v45
	v_mov_b32_e32 v242, v17
	v_mul_f32_e32 v17, v30, v37
	v_mul_f32_e32 v17, v17, v46
	v_mov_b32_e32 v246, v17
	v_mul_f32_e32 v17, v29, v37
	v_mul_f32_e32 v17, v17, v41
	v_mov_b32_e32 v250, v17
	v_lshl_add_u64 v[30:31], v[32:33], 0, s[20:21]
	v_add_u32_e32 v17, 0x6400, v13
	ds_read2_b32 v[32:33], v17 offset1:32
	v_mov_b32_e32 v36, v198
	v_mov_b32_e32 v37, v199
	v_mov_b32_e32 v38, v200
	s_waitcnt lgkmcnt(0)
	v_sub_f32_e32 v34, v28, v32
	ds_read2_b32 v[28:29], v17 offset0:64 offset1:96
	v_sub_f32_e32 v27, v27, v33
	ds_read2_b32 v[32:33], v17 offset0:128 offset1:160
	v_mul_f32_e32 v35, v27, v27
	v_fmac_f32_e32 v35, v34, v34
	s_waitcnt lgkmcnt(0)
; __device__ __forceinline__ bf16_t f2bf(float f) { unsigned u = __float_as_uint(f); u += 0x7FFFu + ((u >> 16) & 1u); return (bf16_t)(u >> 16); }
; __device__ __forceinline__ void df_unit(LAS unsigned char* lds, const bf16_t* qkv, bf16_t* attout, const float* subg, int b_, int h_, int qb_, int wid, int) {
;     ...
;         for (int r = 0; r < 16; ++r) { const int rowc = (r & 3) + 8 * (r >> 2); float ss = 0.f;
; #pragma unroll
;             for (int d = 0; d < 8; ++d) { o[d][r] -= xr[rowc * 256 + d * 32]; ss += o[d][r] * o[d][r]; }
;             ss += __shfl_xor(ss, 1); ss += __shfl_xor(ss, 2); ss += __shfl_xor(ss, 4); ss += __shfl_xor(ss, 8); ss += __shfl_xor(ss, 16);
;             const float rstd = (1.0f - LAMBDA_INIT) / sqrtf(ss * (1.0f / 256.0f) + SUBLN_EPS);
; #pragma unroll
;             for (int d = 0; d < 8; ++d) op[d * 32] = f2bf(o[d][r] * rstd * subg[d * 32 + r32]);
;             op += ((r & 3) == 3 ? 5 : 1) * DM; asm volatile("" : "+v"(op) :: "memory"); } }
	v_sub_f32_e32 v26, v26, v28
	v_sub_f32_e32 v28, v25, v29
	v_sub_f32_e32 v29, v24, v32
	ds_read2_b32 v[24:25], v17 offset0:192 offset1:224
	v_fmac_f32_e32 v35, v26, v26
	v_fmac_f32_e32 v35, v28, v28
	v_fmac_f32_e32 v35, v29, v29
	v_sub_f32_e32 v17, v23, v33
	v_fmac_f32_e32 v35, v17, v17
	s_waitcnt lgkmcnt(0)
	v_sub_f32_e32 v22, v22, v24
	v_fmac_f32_e32 v35, v22, v22
	v_sub_f32_e32 v21, v21, v25
	v_fmac_f32_e32 v35, v21, v21
	s_nop 1
	v_mov_b32_dpp v25, v35 quad_perm:[1,0,3,2] row_mask:0xf bank_mask:0xf
	v_mov_b32_e32 v32, v194
	v_mov_b32_e32 v23, v195
	v_mov_b32_e32 v24, v196
	v_mov_b32_e32 v33, v197
	s_waitcnt lgkmcnt(0)
	v_add_f32_e32 v25, v35, v25
	s_nop 1
	v_mov_b32_dpp v35, v25 quad_perm:[2,3,0,1] row_mask:0xf bank_mask:0xf
	s_waitcnt lgkmcnt(0)
	v_add_f32_e32 v25, v25, v35
	s_nop 1
	v_mov_b32_dpp v35, v25 row_half_mirror row_mask:0xf bank_mask:0xf
	s_waitcnt lgkmcnt(0)
	v_add_f32_e32 v25, v25, v35
	s_nop 1
	v_mov_b32_dpp v35, v25 row_mirror row_mask:0xf bank_mask:0xf
	s_waitcnt lgkmcnt(0)
	v_add_f32_e32 v25, v25, v35
	v_mov_b32_e32 v35, v201
	v_mov_b32_e32 v39, v25
	s_nop 1
	v_permlane16_swap_b32_e32 v39, v25
	s_waitcnt lgkmcnt(0)
	v_add_f32_e32 v25, v25, v39
	v_fmamk_f32 v25, v25, 0x3b800000, v190
	v_mul_f32_e32 v39, 0x4f800000, v25
	v_cmp_gt_f32_e32 vcc, s56, v25
	s_nop 1
	v_cndmask_b32_e32 v25, v25, v39, vcc
	v_sqrt_f32_e32 v39, v25
	s_nop 0
	v_add_u32_e32 v40, -1, v39
	v_fma_f32 v41, -v40, v39, v25
	v_cmp_ge_f32_e64 s[0:1], 0, v41
	v_add_u32_e32 v41, 1, v39
	s_nop 0
	v_cndmask_b32_e64 v40, v39, v40, s[0:1]
	v_fma_f32 v39, -v41, v39, v25
	v_cmp_lt_f32_e64 s[0:1], 0, v39
	s_nop 1
	v_cndmask_b32_e64 v39, v40, v41, s[0:1]
	v_mul_f32_e32 v40, 0x37800000, v39
	v_cndmask_b32_e32 v39, v39, v40, vcc
	v_cmp_class_f32_e32 vcc, v25, v189
	s_nop 1
	v_cndmask_b32_e32 v25, v39, v25, vcc
	v_div_scale_f32 v39, s[0:1], v25, v25, s87
	v_rcp_f32_e32 v40, v39
	s_nop 0
	v_fma_f32 v41, -v39, v40, 1.0
	v_fmac_f32_e32 v40, v41, v40
	v_div_scale_f32 v41, vcc, s87, v25, s87
	v_mul_f32_e32 v42, v41, v40
	v_fma_f32 v43, -v39, v42, v41
	v_fmac_f32_e32 v42, v43, v40
	v_fma_f32 v39, -v39, v42, v41
	v_div_fmas_f32 v39, v39, v40, v42
	v_div_fixup_f32 v25, v39, v25, s87
	v_mul_f32_e32 v27, v27, v25
	v_mul_f32_e32 v17, v17, v25
	v_mul_f32_e32 v17, v17, v37
	v_mul_f32_e32 v34, v34, v25
	v_mul_f32_e32 v32, v32, v34
	v_mul_f32_e32 v23, v23, v27
	v_mov_b32_e32 v227, v23
	v_mul_f32_e32 v23, v26, v25
	v_mul_f32_e32 v23, v24, v23
	v_mov_b32_e32 v231, v23
	v_mul_f32_e32 v23, v28, v25
	v_mul_f32_e32 v23, v33, v23
	v_mov_b32_e32 v235, v23
	v_mul_f32_e32 v23, v29, v25
	v_mul_f32_e32 v23, v36, v23
	v_mov_b32_e32 v239, v23
	v_mov_b32_e32 v243, v17
	v_mul_f32_e32 v17, v22, v25
	v_mul_f32_e32 v17, v17, v38
	v_mov_b32_e32 v247, v17
	v_mul_f32_e32 v17, v21, v25
	v_mul_f32_e32 v17, v17, v35
	v_mov_b32_e32 v223, v32
	v_mov_b32_e32 v251, v17
	v_lshl_add_u64 v[22:23], v[30:31], 0, s[20:21]
	v_add_u32_e32 v17, 0x6800, v13
	ds_read2_b32 v[24:25], v17 offset1:32
	v_mov_b32_e32 v28, v198
	v_mov_b32_e32 v29, v199
	v_mov_b32_e32 v30, v200
	s_waitcnt lgkmcnt(0)
	v_sub_f32_e32 v26, v20, v24
	ds_read2_b32 v[20:21], v17 offset0:64 offset1:96
	v_sub_f32_e32 v19, v19, v25
	ds_read2_b32 v[24:25], v17 offset0:128 offset1:160
	v_mul_f32_e32 v27, v19, v19
	v_fmac_f32_e32 v27, v26, v26
	s_waitcnt lgkmcnt(0)
	v_sub_f32_e32 v18, v18, v20
	v_sub_f32_e32 v20, v16, v21
	ds_read2_b32 v[16:17], v17 offset0:192 offset1:224
	v_fmac_f32_e32 v27, v18, v18
	v_fmac_f32_e32 v27, v20, v20
	v_sub_f32_e32 v15, v15, v24
	v_fmac_f32_e32 v27, v15, v15
	v_sub_f32_e32 v14, v14, v25
	v_fmac_f32_e32 v27, v14, v14
	s_waitcnt lgkmcnt(0)
	v_sub_f32_e32 v11, v11, v16
	v_fmac_f32_e32 v27, v11, v11
	v_sub_f32_e32 v12, v12, v17
	v_fmac_f32_e32 v27, v12, v12
	s_nop 1
	v_mov_b32_dpp v17, v27 quad_perm:[1,0,3,2] row_mask:0xf bank_mask:0xf
	v_mov_b32_e32 v21, v194
	v_mov_b32_e32 v24, v195
	v_mov_b32_e32 v16, v196
	v_mov_b32_e32 v25, v197
	s_waitcnt lgkmcnt(0)
	v_add_f32_e32 v17, v27, v17
	s_nop 1
	v_mov_b32_dpp v27, v17 quad_perm:[2,3,0,1] row_mask:0xf bank_mask:0xf
	s_waitcnt lgkmcnt(0)
	v_add_f32_e32 v17, v17, v27
	s_nop 1
	v_mov_b32_dpp v27, v17 row_half_mirror row_mask:0xf bank_mask:0xf
	s_waitcnt lgkmcnt(0)
	v_add_f32_e32 v17, v17, v27
	s_nop 1
	v_mov_b32_dpp v27, v17 row_mirror row_mask:0xf bank_mask:0xf
	s_waitcnt lgkmcnt(0)
	v_add_f32_e32 v17, v17, v27
	v_mov_b32_e32 v27, v201
	v_mov_b32_e32 v31, v17
	s_nop 1
	v_permlane16_swap_b32_e32 v31, v17
	s_waitcnt lgkmcnt(0)
	v_add_f32_e32 v17, v17, v31
	v_fmamk_f32 v17, v17, 0x3b800000, v190
	v_mul_f32_e32 v31, 0x4f800000, v17
	v_cmp_gt_f32_e32 vcc, s56, v17
	s_nop 1
	v_cndmask_b32_e32 v17, v17, v31, vcc
	v_sqrt_f32_e32 v31, v17
	s_nop 0
	v_add_u32_e32 v32, -1, v31
	v_fma_f32 v33, -v32, v31, v17
	v_cmp_ge_f32_e64 s[0:1], 0, v33
	v_add_u32_e32 v33, 1, v31
	s_nop 0
	v_cndmask_b32_e64 v32, v31, v32, s[0:1]
	v_fma_f32 v31, -v33, v31, v17
	v_cmp_lt_f32_e64 s[0:1], 0, v31
	s_nop 1
	v_cndmask_b32_e64 v31, v32, v33, s[0:1]
	v_mul_f32_e32 v32, 0x37800000, v31
	v_cndmask_b32_e32 v31, v31, v32, vcc
	v_cmp_class_f32_e32 vcc, v17, v189
	s_nop 1
	v_cndmask_b32_e32 v17, v31, v17, vcc
	v_div_scale_f32 v31, s[0:1], v17, v17, s87
	v_rcp_f32_e32 v32, v31
	s_nop 0
	v_fma_f32 v33, -v31, v32, 1.0
	v_fmac_f32_e32 v32, v33, v32
	v_div_scale_f32 v33, vcc, s87, v17, s87
	v_mul_f32_e32 v34, v33, v32
	v_fma_f32 v35, -v31, v34, v33
	v_fmac_f32_e32 v34, v35, v32
	v_fma_f32 v31, -v31, v34, v33
	v_div_fmas_f32 v31, v31, v32, v34
	v_div_fixup_f32 v17, v31, v17, s87
	v_mul_f32_e32 v18, v18, v17
	v_mul_f32_e32 v15, v15, v17
	v_mul_f32_e32 v15, v28, v15
	v_mul_f32_e32 v14, v14, v17
	v_mul_f32_e32 v14, v14, v29
	v_mul_f32_e32 v11, v11, v17
	v_mul_f32_e32 v11, v11, v30
	v_mul_f32_e32 v26, v26, v17
	v_mul_f32_e32 v21, v21, v26
	v_mul_f32_e32 v16, v16, v18
	v_mov_b32_e32 v232, v16
	v_mul_f32_e32 v16, v20, v17
	v_mul_f32_e32 v16, v25, v16
	v_mov_b32_e32 v236, v16
	v_mov_b32_e32 v240, v15
	v_mov_b32_e32 v244, v14
	v_mov_b32_e32 v248, v11
	v_mul_f32_e32 v19, v19, v17
	v_mul_f32_e32 v11, v12, v17
	v_mov_b32_e32 v224, v21
	v_mul_f32_e32 v19, v24, v19
	v_mul_f32_e32 v11, v11, v27
	v_mov_b32_e32 v228, v19
	v_mov_b32_e32 v252, v11
	v_lshl_add_u64 v[14:15], v[22:23], 0, s[20:21]
	v_add_u32_e32 v16, 0x6c00, v13
	ds_read2_b32 v[12:13], v16 offset1:32
	v_mov_b32_e32 v19, v198
	v_mov_b32_e32 v20, v199
	v_mov_b32_e32 v21, v200
	s_waitcnt lgkmcnt(0)
; __device__ __forceinline__ void df_unit(LAS unsigned char* lds, const bf16_t* qkv, bf16_t* attout, const float* subg, int b_, int h_, int qb_, int wid, int) {
;     ...
;         for (int r = 0; r < 16; ++r) { const int rowc = (r & 3) + 8 * (r >> 2); float ss = 0.f;
; #pragma unroll
;             for (int d = 0; d < 8; ++d) { o[d][r] -= xr[rowc * 256 + d * 32]; ss += o[d][r] * o[d][r]; }
;             ss += __shfl_xor(ss, 1); ss += __shfl_xor(ss, 2); ss += __shfl_xor(ss, 4); ss += __shfl_xor(ss, 8); ss += __shfl_xor(ss, 16);
	v_sub_f32_e32 v17, v10, v12
	ds_read2_b32 v[10:11], v16 offset0:64 offset1:96
	v_sub_f32_e32 v9, v9, v13
	ds_read2_b32 v[12:13], v16 offset0:128 offset1:160
	v_mul_f32_e32 v18, v9, v9
	v_fmac_f32_e32 v18, v17, v17
	s_waitcnt lgkmcnt(0)
	v_sub_f32_e32 v8, v8, v10
	v_sub_f32_e32 v10, v7, v11
	v_sub_f32_e32 v11, v6, v12
	v_mov_b32_e32 v12, v194
	ds_read2_b32 v[6:7], v16 offset0:192 offset1:224
	v_sub_f32_e32 v5, v5, v13
	v_mov_b32_e32 v13, v195
	v_mov_b32_e32 v16, v197
	v_fmac_f32_e32 v18, v8, v8
	s_waitcnt lgkmcnt(0)
	v_sub_f32_e32 v4, v4, v6
	v_mov_b32_e32 v6, v196
	v_fmac_f32_e32 v18, v10, v10
	v_fmac_f32_e32 v18, v11, v11
	v_fmac_f32_e32 v18, v5, v5
	v_fmac_f32_e32 v18, v4, v4
	v_sub_f32_e32 v0, v0, v7
	v_fmac_f32_e32 v18, v0, v0
	s_nop 1
	v_mov_b32_dpp v7, v18 quad_perm:[1,0,3,2] row_mask:0xf bank_mask:0xf
	v_mov_b32_e32 v2, v201
	s_waitcnt lgkmcnt(0)
	v_add_f32_e32 v7, v18, v7
	s_nop 1
	v_mov_b32_dpp v18, v7 quad_perm:[2,3,0,1] row_mask:0xf bank_mask:0xf
	s_waitcnt lgkmcnt(0)
	v_add_f32_e32 v7, v7, v18
	s_nop 1
	v_mov_b32_dpp v18, v7 row_half_mirror row_mask:0xf bank_mask:0xf
	s_waitcnt lgkmcnt(0)
	v_add_f32_e32 v7, v7, v18
	s_nop 1
	v_mov_b32_dpp v18, v7 row_mirror row_mask:0xf bank_mask:0xf
	s_waitcnt lgkmcnt(0)
	v_add_f32_e32 v7, v7, v18
	v_mov_b32_e32 v3, v7
	s_nop 1
	v_permlane16_swap_b32_e32 v3, v7
	s_waitcnt lgkmcnt(0)
; __device__ __forceinline__ bf16_t f2bf(float f) { unsigned u = __float_as_uint(f); u += 0x7FFFu + ((u >> 16) & 1u); return (bf16_t)(u >> 16); }
; __device__ __forceinline__ void df_unit(LAS unsigned char* lds, const bf16_t* qkv, bf16_t* attout, const float* subg, int b_, int h_, int qb_, int wid, int) {
;     ...
;         for (int r = 0; r < 16; ++r) { const int rowc = (r & 3) + 8 * (r >> 2); float ss = 0.f;
; #pragma unroll
;             for (int d = 0; d < 8; ++d) { o[d][r] -= xr[rowc * 256 + d * 32]; ss += o[d][r] * o[d][r]; }
;             ss += __shfl_xor(ss, 1); ss += __shfl_xor(ss, 2); ss += __shfl_xor(ss, 4); ss += __shfl_xor(ss, 8); ss += __shfl_xor(ss, 16);
;             const float rstd = (1.0f - LAMBDA_INIT) / sqrtf(ss * (1.0f / 256.0f) + SUBLN_EPS);
; #pragma unroll
;             for (int d = 0; d < 8; ++d) op[d * 32] = f2bf(o[d][r] * rstd * subg[d * 32 + r32]);
;             op += ((r & 3) == 3 ? 5 : 1) * DM; asm volatile("" : "+v"(op) :: "memory"); } }
	v_add_f32_e32 v3, v7, v3
	v_fmamk_f32 v3, v3, 0x3b800000, v190
	v_mul_f32_e32 v7, 0x4f800000, v3
	v_cmp_gt_f32_e32 vcc, s56, v3
	s_nop 1
	v_cndmask_b32_e32 v3, v3, v7, vcc
	v_sqrt_f32_e32 v7, v3
	s_nop 0
	v_add_u32_e32 v18, -1, v7
	v_fma_f32 v22, -v18, v7, v3
	v_cmp_ge_f32_e64 s[0:1], 0, v22
	v_add_u32_e32 v22, 1, v7
	s_nop 0
	v_cndmask_b32_e64 v18, v7, v18, s[0:1]
	v_fma_f32 v7, -v22, v7, v3
	v_cmp_lt_f32_e64 s[0:1], 0, v7
	s_nop 1
	v_cndmask_b32_e64 v7, v18, v22, s[0:1]
	v_mul_f32_e32 v18, 0x37800000, v7
	v_cndmask_b32_e32 v7, v7, v18, vcc
	v_cmp_class_f32_e32 vcc, v3, v189
	s_nop 1
	v_cndmask_b32_e32 v3, v7, v3, vcc
	v_div_scale_f32 v7, s[0:1], v3, v3, s87
	v_rcp_f32_e32 v18, v7
	s_nop 0
	v_fma_f32 v22, -v7, v18, 1.0
	v_fmac_f32_e32 v18, v22, v18
	v_div_scale_f32 v22, vcc, s87, v3, s87
	v_mul_f32_e32 v23, v22, v18
	v_fma_f32 v24, -v7, v23, v22
	v_fmac_f32_e32 v23, v24, v18
	v_fma_f32 v7, -v7, v23, v22
	v_div_fmas_f32 v7, v7, v18, v23
	v_div_fixup_f32 v3, v7, v3, s87
	v_mul_f32_e32 v7, v17, v3
	v_mul_f32_e32 v7, v12, v7
	v_mov_b32_e32 v225, v7
	v_mul_f32_e32 v7, v9, v3
	v_mul_f32_e32 v7, v13, v7
	v_mov_b32_e32 v229, v7
	v_mul_f32_e32 v7, v8, v3
	v_mul_f32_e32 v6, v6, v7
	v_mov_b32_e32 v233, v6
	v_mul_f32_e32 v6, v10, v3
	v_mul_f32_e32 v6, v16, v6
	v_mov_b32_e32 v237, v6
	v_mul_f32_e32 v6, v11, v3
	v_mul_f32_e32 v6, v19, v6
	v_mul_f32_e32 v5, v5, v3
	v_mov_b32_e32 v241, v6
	v_mul_f32_e32 v5, v5, v20
	v_mul_f32_e32 v4, v4, v3
	v_mul_f32_e32 v0, v0, v3
	v_mov_b32_e32 v245, v5
	v_mul_f32_e32 v4, v4, v21
	v_mul_f32_e32 v0, v0, v2
	v_mov_b32_e32 v249, v4
	v_mov_b32_e32 v253, v0
	v_cvt_pk_bf16_f32 v222, v222, v223
	v_cvt_pk_bf16_f32 v226, v226, v227
	v_cvt_pk_bf16_f32 v230, v230, v231
	v_cvt_pk_bf16_f32 v234, v234, v235
	v_cvt_pk_bf16_f32 v238, v238, v239
	v_cvt_pk_bf16_f32 v242, v242, v243
	v_cvt_pk_bf16_f32 v246, v246, v247
	v_cvt_pk_bf16_f32 v250, v250, v251
	v_cvt_pk_bf16_f32 v224, v224, v225
	v_cvt_pk_bf16_f32 v228, v228, v229
	v_cvt_pk_bf16_f32 v232, v232, v233
	v_cvt_pk_bf16_f32 v236, v236, v237
	v_cvt_pk_bf16_f32 v240, v240, v241
	v_cvt_pk_bf16_f32 v244, v244, v245
	v_cvt_pk_bf16_f32 v248, v248, v249
	v_cvt_pk_bf16_f32 v252, v252, v253
	v_mov_b32_dpp v223, v222 quad_perm:[1,0,3,2] row_mask:0xf bank_mask:0xf
	v_mov_b32_dpp v227, v226 quad_perm:[1,0,3,2] row_mask:0xf bank_mask:0xf
	v_mov_b32_dpp v231, v230 quad_perm:[1,0,3,2] row_mask:0xf bank_mask:0xf
	v_mov_b32_dpp v235, v234 quad_perm:[1,0,3,2] row_mask:0xf bank_mask:0xf
	v_mov_b32_dpp v239, v238 quad_perm:[1,0,3,2] row_mask:0xf bank_mask:0xf
	v_mov_b32_dpp v243, v242 quad_perm:[1,0,3,2] row_mask:0xf bank_mask:0xf
	v_mov_b32_dpp v247, v246 quad_perm:[1,0,3,2] row_mask:0xf bank_mask:0xf
	v_mov_b32_dpp v251, v250 quad_perm:[1,0,3,2] row_mask:0xf bank_mask:0xf
	v_mov_b32_dpp v225, v224 quad_perm:[1,0,3,2] row_mask:0xf bank_mask:0xf
	v_mov_b32_dpp v229, v228 quad_perm:[1,0,3,2] row_mask:0xf bank_mask:0xf
	v_mov_b32_dpp v233, v232 quad_perm:[1,0,3,2] row_mask:0xf bank_mask:0xf
	v_mov_b32_dpp v237, v236 quad_perm:[1,0,3,2] row_mask:0xf bank_mask:0xf
	v_mov_b32_dpp v241, v240 quad_perm:[1,0,3,2] row_mask:0xf bank_mask:0xf
	v_mov_b32_dpp v245, v244 quad_perm:[1,0,3,2] row_mask:0xf bank_mask:0xf
	v_mov_b32_dpp v249, v248 quad_perm:[1,0,3,2] row_mask:0xf bank_mask:0xf
	v_mov_b32_dpp v253, v252 quad_perm:[1,0,3,2] row_mask:0xf bank_mask:0xf
	v_perm_b32 v222, v222, v223, v204
	v_perm_b32 v226, v226, v227, v204
	v_perm_b32 v230, v230, v231, v204
	v_perm_b32 v234, v234, v235, v204
	v_perm_b32 v238, v238, v239, v204
	v_perm_b32 v242, v242, v243, v204
	v_perm_b32 v246, v246, v247, v204
	v_perm_b32 v250, v250, v251, v204
	v_perm_b32 v224, v224, v225, v204
	v_perm_b32 v228, v228, v229, v204
	v_perm_b32 v232, v232, v233, v204
	v_perm_b32 v236, v236, v237, v204
	v_perm_b32 v240, v240, v241, v204
	v_perm_b32 v244, v244, v245, v204
	v_perm_b32 v248, v248, v249, v204
	v_perm_b32 v252, v252, v253, v204
	v_cndmask_b32_e64 v223, v224, v222, s[98:99]
	v_cndmask_b32_e64 v227, v228, v226, s[98:99]
	v_cndmask_b32_e64 v231, v232, v230, s[98:99]
	v_cndmask_b32_e64 v235, v236, v234, s[98:99]
	v_cndmask_b32_e64 v239, v240, v238, s[98:99]
	v_cndmask_b32_e64 v243, v244, v242, s[98:99]
	v_cndmask_b32_e64 v247, v248, v246, s[98:99]
	v_cndmask_b32_e64 v251, v252, v250, s[98:99]
	v_mov_b32_dpp v225, v223 quad_perm:[2,3,0,1] row_mask:0xf bank_mask:0xf
	v_mov_b32_dpp v229, v227 quad_perm:[2,3,0,1] row_mask:0xf bank_mask:0xf
	v_mov_b32_dpp v233, v231 quad_perm:[2,3,0,1] row_mask:0xf bank_mask:0xf
	v_mov_b32_dpp v237, v235 quad_perm:[2,3,0,1] row_mask:0xf bank_mask:0xf
	v_mov_b32_dpp v241, v239 quad_perm:[2,3,0,1] row_mask:0xf bank_mask:0xf
	v_mov_b32_dpp v245, v243 quad_perm:[2,3,0,1] row_mask:0xf bank_mask:0xf
	v_mov_b32_dpp v249, v247 quad_perm:[2,3,0,1] row_mask:0xf bank_mask:0xf
	v_mov_b32_dpp v253, v251 quad_perm:[2,3,0,1] row_mask:0xf bank_mask:0xf
	v_cndmask_b32_e64 v223, v225, v224, s[98:99]
	v_cndmask_b32_e64 v227, v229, v228, s[98:99]
	v_cndmask_b32_e64 v231, v233, v232, s[98:99]
	v_cndmask_b32_e64 v235, v237, v236, s[98:99]
	v_cndmask_b32_e64 v239, v241, v240, s[98:99]
	v_cndmask_b32_e64 v243, v245, v244, s[98:99]
	v_cndmask_b32_e64 v247, v249, v248, s[98:99]
	v_cndmask_b32_e64 v251, v253, v252, s[98:99]
	v_cndmask_b32_e64 v222, v222, v225, s[98:99]
	v_cndmask_b32_e64 v226, v226, v229, s[98:99]
	v_cndmask_b32_e64 v230, v230, v233, s[98:99]
	v_cndmask_b32_e64 v234, v234, v237, s[98:99]
	v_cndmask_b32_e64 v238, v238, v241, s[98:99]
	v_cndmask_b32_e64 v242, v242, v245, s[98:99]
	v_cndmask_b32_e64 v246, v246, v249, s[98:99]
	v_cndmask_b32_e64 v250, v250, v253, s[98:99]
	global_store_dwordx2 v[202:203], v[222:223], off offset:2048
	global_store_dwordx2 v[202:203], v[226:227], off offset:2112
	global_store_dwordx2 v[202:203], v[230:231], off offset:2176
	global_store_dwordx2 v[202:203], v[234:235], off offset:2240
	global_store_dwordx2 v[202:203], v[238:239], off offset:2304
	global_store_dwordx2 v[202:203], v[242:243], off offset:2368
	global_store_dwordx2 v[202:203], v[246:247], off offset:2432
	global_store_dwordx2 v[202:203], v[250:251], off offset:2496
	v_lshl_add_u64 v[202:203], v[202:203], 0, s[100:101]
	v_lshl_add_u64 v[2:3], v[14:15], 0, s[22:23]
	s_branch .LBB0_260
